# P6 tail: last K pair-iteration skips the 14 dummy stage loads and instead requests the fused epilogue's first 8 operands (bias, x1b, pp) into free VGPRs; epilogue head uses them; on top of v23
# baseline (speedup 1.0000x reference)
; #define PG8_STAGE(bufoff, gbase, voff) do { _Pragma("unroll") for (int _i = 0; _i < 2; ++_i) \
;         __builtin_amdgcn_global_load_lds((const unsigned*)((const char*)(gbase) + (voff)[_i]), (PG8_LAS unsigned*)(lds + (bufoff) + ldsw + _i * 8192), 16, 0, 0); } while (0)
; #define PG8_LDA(dst, b, h) do { _Pragma("unroll") for (int m = 0; m < 4; ++m) _Pragma("unroll") for (int k = 0; k < 2; ++k) dst[m][k] = *(const PG8_LAS bf16x8*)(lds + PG8_SA(b, h) + aoff + m * 2048 + k * 1024); } while (0)
; #define PG8_WAIT_V(n) asm volatile("s_waitcnt vmcnt(" #n ")" ::: "memory")
; #define PG8_BAR __builtin_amdgcn_s_barrier()
;     __device__ __forceinline__ void fused(f32x4 (&acc)[2][2][4][2], const Unit& u, int wr, int wc, int fr, int fq, PG8_LAS unsigned char* lds, int wid, int lane) const {
;     ...
;             const f32x4 b0 = *(const f32x4*)(gb + col0 + bj * HALF), b1 = *(const f32x4*)(gb + col0 + bj * HALF + 4);
; #pragma unroll
;             for (int ai = 0; ai < 2; ++ai)
; #pragma unroll
;                 for (int m = 0; m < 4; ++m) { acc[ai][bj][m][0] += b0; acc[ai][bj][m][1] += b1; } }
; #pragma unroll
;         for (int ai = 0; ai < 2; ++ai)
; #pragma unroll
;             for (int m = 0; m < 4; ++m) { const size_t off = (size_t)(u.pm * BM + ai * HALF + wr * 64 + m * 16 + fr) * 1024 + col0;
; #pragma unroll
;                 for (int bj = 0; bj < 2; ++bj) {
;                     const u32x4 xw = *(const u32x4*)(x1b + off + bj * HALF);
;                     f32x4 x0, x1;
;                     x0[0] = __uint_as_float(xw.x << 16); x0[1] = __uint_as_float(xw.x & 0xffff0000u); x0[2] = __uint_as_float(xw.y << 16); x0[3] = __uint_as_float(xw.y & 0xffff0000u);
;                     x1[0] = __uint_as_float(xw.z << 16); x1[1] = __uint_as_float(xw.z & 0xffff0000u); x1[2] = __uint_as_float(xw.w << 16); x1[3] = __uint_as_float(xw.w & 0xffff0000u);
;                     const u32x4 pw = *(const u32x4*)(pp + off + bj * HALF);
; template <class Epi, class Sched, bool ALIGN_EPI = false, bool SP2 = false>
; __device__ __forceinline__ void gemm_phase(PG8_LAS unsigned char* lds, const Gemm g, const Sched& S, const Epi& E, int wid_in) {
;     ...
;             PG8_LDB(B0, 0, 0); PG8_LDB(B1, 0, 1); PG8_SCHED; PG8_LDA(At, 0, 0); PG8_STAGE(PG8_SA(1, 1), a1 + hstep, voffA);
;             PG8_WAIT_V(8); PG8_WAIT_L(0); PG8_BAR; PG8_MMA(0, 0, At, B0); PG8_MMA(0, 1, At, B1); PG8_BAR; PG8_SCHED;
.LBB0_986:
	v_add_u32_e32 v155, s43, v153
	ds_read_b128 v[156:159], v155
	ds_read_b128 v[160:163], v155 offset:1024
	ds_read_b128 v[164:167], v155 offset:2048
	ds_read_b128 v[168:171], v155 offset:3072
	v_add_u32_e32 v155, s44, v153
	s_add_u32 s28, s10, s26
	ds_read_b128 v[172:175], v155
	ds_read_b128 v[176:179], v155 offset:1024
	ds_read_b128 v[180:183], v155 offset:2048
	ds_read_b128 v[184:187], v155 offset:3072
	s_addc_u32 s29, s11, s27
	s_add_u32 s28, s28, 0x100
	s_addc_u32 s29, s29, 0
	s_add_u32 s49, s23, s26
	s_addc_u32 s50, s45, s27
	s_cmpk_eq_i32 s26, 0x700
	s_cselect_b32 s31, s19, s29
	s_cselect_b32 s30, s46, s28
	s_cselect_b32 s29, s17, s50
	s_cselect_b32 s28, s47, s49
	v_lshl_add_u64 v[220:221], v[144:145], 0, s[26:27]
	s_add_i32 m0, s36, 0xc000
	ds_read_b128 v[188:191], v154
	ds_read_b128 v[192:195], v154 offset:1024
	ds_read_b128 v[196:199], v154 offset:2048
	ds_read_b128 v[200:203], v154 offset:3072
	ds_read_b128 v[204:207], v154 offset:4096
	ds_read_b128 v[208:211], v154 offset:5120
	ds_read_b128 v[212:215], v154 offset:6144
	ds_read_b128 v[216:219], v154 offset:7168
	global_load_lds_dwordx4 v[220:221], off
	v_lshl_add_u64 v[220:221], v[146:147], 0, s[26:27]
	s_add_i32 m0, s36, 0xe000
	s_nop 0
	global_load_lds_dwordx4 v[220:221], off
	s_cmpk_eq_i32 s26, 0x700
	s_cbranch_scc0 .Lp6t_noE
	v_ashrrev_i32_e32 v220, 1, v150
	s_lshl_b32 s98, s5, 5
	s_lshl_b32 s99, s6, 8
	v_and_b32_e32 v220, -8, v220
	s_or_b32 s98, s99, s98
	v_add_u32_e32 v220, s98, v220
	v_mov_b32_e32 v222, s54
	v_ashrrev_i32_e32 v221, 31, v220
	v_mov_b32_e32 v223, s55
	s_lshl_b32 s98, s4, 8
	v_lshl_add_u64 v[222:223], v[220:221], 2, v[222:223]
	s_add_i32 s98, s98, s12
	global_load_dwordx4 v[230:233], v[222:223], off
	global_load_dwordx4 v[234:237], v[222:223], off offset:16
	global_load_dwordx4 v[238:241], v[222:223], off offset:512
	global_load_dwordx4 v[242:245], v[222:223], off offset:528
	v_or_b32_e32 v224, s98, v152
	s_add_u32 s100, s96, 0xdc00000
	v_ashrrev_i32_e32 v225, 31, v224
	s_addc_u32 s101, s97, 0
	v_lshlrev_b64 v[224:225], 10, v[224:225]
	v_lshl_add_u64 v[224:225], v[224:225], 0, v[220:221]
	v_lshlrev_b64 v[224:225], 1, v[224:225]
	v_lshl_add_u64 v[220:221], s[8:9], 0, v[224:225]
	v_lshl_add_u64 v[224:225], s[100:101], 0, v[224:225]
	global_load_dwordx4 v[246:249], v[220:221], off
	global_load_dwordx2 v[250:251], v[224:225], off
	global_load_dwordx2 v[254:255], v[224:225], off offset:8
	global_load_dwordx4 v[136:139], v[220:221], off offset:256
	global_load_dwordx4 v[140:143], v[224:225], off offset:256
.Lp6t_noE:
	s_cmpk_eq_i32 s26, 0x700
	s_cbranch_scc1 .Lp6t_w0a
	s_waitcnt vmcnt(8)
	s_branch .Lp6t_w0b
.Lp6t_w0a:
	s_waitcnt vmcnt(17)
.Lp6t_w0b:
	s_waitcnt lgkmcnt(0)
	s_barrier
	s_setprio 1
	s_waitcnt lgkmcnt(0)
	v_mfma_f32_16x16x32_bf16 v[60:63], v[156:159], v[188:191], v[60:63]
	v_mfma_f32_16x16x32_bf16 v[56:59], v[164:167], v[188:191], v[56:59]
	v_mfma_f32_16x16x32_bf16 v[88:91], v[156:159], v[196:199], v[88:91]
	v_mfma_f32_16x16x32_bf16 v[84:87], v[164:167], v[196:199], v[84:87]
	v_mfma_f32_16x16x32_bf16 v[108:111], v[156:159], v[204:207], v[108:111]
	v_mfma_f32_16x16x32_bf16 v[104:107], v[164:167], v[204:207], v[104:107]
	v_mfma_f32_16x16x32_bf16 v[124:127], v[156:159], v[212:215], v[124:127]
	v_mfma_f32_16x16x32_bf16 v[120:123], v[164:167], v[212:215], v[120:123]
	v_mfma_f32_16x16x32_bf16 v[60:63], v[160:163], v[192:195], v[60:63]
	v_mfma_f32_16x16x32_bf16 v[56:59], v[168:171], v[192:195], v[56:59]
	v_mfma_f32_16x16x32_bf16 v[88:91], v[160:163], v[200:203], v[88:91]
	v_mfma_f32_16x16x32_bf16 v[84:87], v[168:171], v[200:203], v[84:87]
	v_mfma_f32_16x16x32_bf16 v[108:111], v[160:163], v[208:211], v[108:111]
	v_mfma_f32_16x16x32_bf16 v[104:107], v[168:171], v[208:211], v[104:107]
	v_mfma_f32_16x16x32_bf16 v[124:127], v[160:163], v[216:219], v[124:127]
	v_mfma_f32_16x16x32_bf16 v[120:123], v[168:171], v[216:219], v[120:123]
	s_setprio 0
	s_setprio 1
	v_mfma_f32_16x16x32_bf16 v[36:39], v[172:175], v[188:191], v[36:39]
	v_mfma_f32_16x16x32_bf16 v[32:35], v[180:183], v[188:191], v[32:35]
	v_mfma_f32_16x16x32_bf16 v[68:71], v[172:175], v[196:199], v[68:71]
	v_mfma_f32_16x16x32_bf16 v[64:67], v[180:183], v[196:199], v[64:67]
	v_mfma_f32_16x16x32_bf16 v[100:103], v[172:175], v[204:207], v[100:103]
	v_mfma_f32_16x16x32_bf16 v[96:99], v[180:183], v[204:207], v[96:99]
	v_mfma_f32_16x16x32_bf16 v[116:119], v[172:175], v[212:215], v[116:119]
	v_mfma_f32_16x16x32_bf16 v[112:115], v[180:183], v[212:215], v[112:115]
	v_mfma_f32_16x16x32_bf16 v[36:39], v[176:179], v[192:195], v[36:39]
	v_mfma_f32_16x16x32_bf16 v[32:35], v[184:187], v[192:195], v[32:35]
	v_mfma_f32_16x16x32_bf16 v[68:71], v[176:179], v[200:203], v[68:71]
	v_mfma_f32_16x16x32_bf16 v[64:67], v[184:187], v[200:203], v[64:67]
	v_mfma_f32_16x16x32_bf16 v[100:103], v[176:179], v[208:211], v[100:103]
	v_mfma_f32_16x16x32_bf16 v[96:99], v[184:187], v[208:211], v[96:99]
	v_mfma_f32_16x16x32_bf16 v[116:119], v[176:179], v[216:219], v[116:119]
	v_mfma_f32_16x16x32_bf16 v[112:115], v[184:187], v[216:219], v[112:115]
	s_setprio 0
	s_barrier
	s_add_i32 s49, s43, s35
	v_lshl_add_u64 v[220:221], s[28:29], 0, v[130:131]
	s_mov_b32 m0, s49
	ds_read_b128 v[188:191], v154 offset:16384
	ds_read_b128 v[192:195], v154 offset:17408
	ds_read_b128 v[196:199], v154 offset:18432
	ds_read_b128 v[200:203], v154 offset:19456
	ds_read_b128 v[204:207], v154 offset:20480
	ds_read_b128 v[208:211], v154 offset:21504
	ds_read_b128 v[212:215], v154 offset:22528
	ds_read_b128 v[216:219], v154 offset:23552
	s_cmpk_eq_i32 s26, 0x700
	s_cbranch_scc1 .Lp6t_s1
	global_load_lds_dwordx4 v[220:221], off
	s_add_i32 m0, s49, 0x2000
	s_add_u32 s50, s28, 0x40000
	v_lshl_add_u64 v[222:223], s[28:29], 0, v[134:135]
	s_addc_u32 s51, s29, 0
	s_add_i32 s49, s44, s35
	global_load_lds_dwordx4 v[222:223], off
	v_lshl_add_u64 v[224:225], s[50:51], 0, v[130:131]
	s_mov_b32 m0, s49
	v_lshl_add_u64 v[226:227], s[30:31], 0, v[132:133]
	global_load_lds_dwordx4 v[224:225], off
	v_lshl_add_u64 v[224:225], s[50:51], 0, v[134:135]
	s_add_i32 m0, s49, 0x2000
	s_nop 0
	global_load_lds_dwordx4 v[224:225], off
	v_lshl_add_u64 v[224:225], s[30:31], 0, v[128:129]
	s_mov_b32 m0, s36
	s_nop 0
	global_load_lds_dwordx4 v[224:225], off
	s_mov_b32 m0, s37
	s_nop 0
	global_load_lds_dwordx4 v[226:227], off

; #define PG8_STAGE(bufoff, gbase, voff) do { _Pragma("unroll") for (int _i = 0; _i < 2; ++_i) \
;         __builtin_amdgcn_global_load_lds((const unsigned*)((const char*)(gbase) + (voff)[_i]), (PG8_LAS unsigned*)(lds + (bufoff) + ldsw + _i * 8192), 16, 0, 0); } while (0)
; #define PG8_LDA(dst, b, h) do { _Pragma("unroll") for (int m = 0; m < 4; ++m) _Pragma("unroll") for (int k = 0; k < 2; ++k) dst[m][k] = *(const PG8_LAS bf16x8*)(lds + PG8_SA(b, h) + aoff + m * 2048 + k * 1024); } while (0)
; #define PG8_MMA(ai, bj, At, Bt) do { __builtin_amdgcn_s_setprio(1); _Pragma("unroll") for (int m = 0; m < 4; ++m) _Pragma("unroll") for (int n = 0; n < 2; ++n) _Pragma("unroll") for (int k = 0; k < 2; ++k) \
;         acc[ai][bj][m][n] = __builtin_amdgcn_mfma_f32_16x16x32_bf16(Bt[n][k], At[m][k], acc[ai][bj][m][n], 0, 0, 0); __builtin_amdgcn_s_setprio(0); } while (0)
; #define PG8_WAIT_V(n) asm volatile("s_waitcnt vmcnt(" #n ")" ::: "memory")
; #define PG8_WAIT_L(n) asm volatile("s_waitcnt lgkmcnt(" #n ")" ::: "memory")
; #define PG8_BAR __builtin_amdgcn_s_barrier()
; #define PG8_SCHED __builtin_amdgcn_sched_barrier(0)
; template <class Epi, class Sched, bool ALIGN_EPI = false, bool SP2 = false>
; __device__ __forceinline__ void gemm_phase(PG8_LAS unsigned char* lds, const Gemm g, const Sched& S, const Epi& E, int wid_in) {
;     ...
;             PG8_WAIT_V(8); PG8_WAIT_L(0); PG8_BAR; PG8_MMA(0, 0, At, B0); PG8_MMA(0, 1, At, B1); PG8_BAR; PG8_SCHED;
;             PG8_LDA(At, 0, 1); PG8_STAGE(PG8_SB(0, 0), b2, voffB); PG8_STAGE(PG8_SB(0, 1), b2 + hstep, voffB); PG8_STAGE(PG8_SA(0, 0), a2, voffA);
;             PG8_WAIT_V(8); PG8_WAIT_L(0); PG8_BAR; PG8_MMA(1, 0, At, B0); PG8_MMA(1, 1, At, B1); PG8_BAR; PG8_SCHED;
.Lp6t_w1a:
	s_waitcnt vmcnt(11)
.Lp6t_w1b:
	s_waitcnt lgkmcnt(0)
	s_barrier
	s_setprio 1
	s_waitcnt lgkmcnt(0)
	v_mfma_f32_16x16x32_bf16 v[92:95], v[156:159], v[188:191], v[92:95]
	v_mfma_f32_16x16x32_bf16 v[80:83], v[164:167], v[188:191], v[80:83]
	v_mfma_f32_16x16x32_bf16 v[52:55], v[156:159], v[196:199], v[52:55]
	v_mfma_f32_16x16x32_bf16 v[48:51], v[164:167], v[196:199], v[48:51]
	v_mfma_f32_16x16x32_bf16 v[28:31], v[156:159], v[204:207], v[28:31]
	v_mfma_f32_16x16x32_bf16 v[24:27], v[164:167], v[204:207], v[24:27]
	v_mfma_f32_16x16x32_bf16 v[12:15], v[156:159], v[212:215], v[12:15]
	v_mfma_f32_16x16x32_bf16 v[8:11], v[164:167], v[212:215], v[8:11]
	v_mfma_f32_16x16x32_bf16 v[92:95], v[160:163], v[192:195], v[92:95]
	v_mfma_f32_16x16x32_bf16 v[80:83], v[168:171], v[192:195], v[80:83]
	v_mfma_f32_16x16x32_bf16 v[52:55], v[160:163], v[200:203], v[52:55]
	v_mfma_f32_16x16x32_bf16 v[48:51], v[168:171], v[200:203], v[48:51]
	v_mfma_f32_16x16x32_bf16 v[28:31], v[160:163], v[208:211], v[28:31]
	v_mfma_f32_16x16x32_bf16 v[24:27], v[168:171], v[208:211], v[24:27]
	v_mfma_f32_16x16x32_bf16 v[12:15], v[160:163], v[216:219], v[12:15]
	v_mfma_f32_16x16x32_bf16 v[8:11], v[168:171], v[216:219], v[8:11]
	s_setprio 0
	s_setprio 1
	v_mfma_f32_16x16x32_bf16 v[76:79], v[172:175], v[188:191], v[76:79]
	v_mfma_f32_16x16x32_bf16 v[72:75], v[180:183], v[188:191], v[72:75]
	v_mfma_f32_16x16x32_bf16 v[44:47], v[172:175], v[196:199], v[44:47]
	v_mfma_f32_16x16x32_bf16 v[40:43], v[180:183], v[196:199], v[40:43]
	v_mfma_f32_16x16x32_bf16 v[20:23], v[172:175], v[204:207], v[20:23]
	v_mfma_f32_16x16x32_bf16 v[16:19], v[180:183], v[204:207], v[16:19]
	v_mfma_f32_16x16x32_bf16 v[4:7], v[172:175], v[212:215], v[4:7]
	v_mfma_f32_16x16x32_bf16 v[0:3], v[180:183], v[212:215], v[0:3]
	v_mfma_f32_16x16x32_bf16 v[76:79], v[176:179], v[192:195], v[76:79]
	v_mfma_f32_16x16x32_bf16 v[72:75], v[184:187], v[192:195], v[72:75]
	v_mfma_f32_16x16x32_bf16 v[44:47], v[176:179], v[200:203], v[44:47]
	v_mfma_f32_16x16x32_bf16 v[40:43], v[184:187], v[200:203], v[40:43]
	v_mfma_f32_16x16x32_bf16 v[20:23], v[176:179], v[208:211], v[20:23]
	v_mfma_f32_16x16x32_bf16 v[16:19], v[184:187], v[208:211], v[16:19]
	v_mfma_f32_16x16x32_bf16 v[4:7], v[176:179], v[216:219], v[4:7]
	v_mfma_f32_16x16x32_bf16 v[0:3], v[184:187], v[216:219], v[0:3]
	s_setprio 0
	s_barrier
	s_add_i32 s49, 0, 0x18000
	v_add_u32_e32 v155, s49, v153
	s_add_i32 s50, 0, 0x1c000
	ds_read_b128 v[156:159], v155
	ds_read_b128 v[160:163], v155 offset:1024
	ds_read_b128 v[164:167], v155 offset:2048
	ds_read_b128 v[168:171], v155 offset:3072
	v_add_u32_e32 v155, s50, v153
	ds_read_b128 v[172:175], v155
	ds_read_b128 v[176:179], v155 offset:1024
	ds_read_b128 v[180:183], v155 offset:2048
	ds_read_b128 v[184:187], v155 offset:3072
	s_add_u32 s30, s30, 0x40000
	s_addc_u32 s31, s31, 0
	s_mov_b32 m0, s38
	v_lshl_add_u64 v[228:229], s[30:31], 0, v[128:129]
	ds_read_b128 v[188:191], v154 offset:32768
	ds_read_b128 v[192:195], v154 offset:33792
	ds_read_b128 v[196:199], v154 offset:34816
	ds_read_b128 v[200:203], v154 offset:35840
	ds_read_b128 v[204:207], v154 offset:36864
	ds_read_b128 v[208:211], v154 offset:37888
	ds_read_b128 v[212:215], v154 offset:38912
	ds_read_b128 v[216:219], v154 offset:39936
	s_cmpk_eq_i32 s26, 0x700
	s_cbranch_scc1 .Lp6t_s2
	global_load_lds_dwordx4 v[228:229], off
	v_lshl_add_u64 v[228:229], s[30:31], 0, v[132:133]
	s_mov_b32 m0, s39
	s_nop 0
	global_load_lds_dwordx4 v[228:229], off

; #define PG8_STAGE(bufoff, gbase, voff) do { _Pragma("unroll") for (int _i = 0; _i < 2; ++_i) \
;         __builtin_amdgcn_global_load_lds((const unsigned*)((const char*)(gbase) + (voff)[_i]), (PG8_LAS unsigned*)(lds + (bufoff) + ldsw + _i * 8192), 16, 0, 0); } while (0)
; #define PG8_LDA(dst, b, h) do { _Pragma("unroll") for (int m = 0; m < 4; ++m) _Pragma("unroll") for (int k = 0; k < 2; ++k) dst[m][k] = *(const PG8_LAS bf16x8*)(lds + PG8_SA(b, h) + aoff + m * 2048 + k * 1024); } while (0)
; #define PG8_LDB(dst, b, h) do { _Pragma("unroll") for (int n = 0; n < 2; ++n) _Pragma("unroll") for (int k = 0; k < 2; ++k) dst[n][k] = *(const PG8_LAS bf16x8*)(lds + PG8_SB(b, h) + boff + n * 2048 + k * 1024); } while (0)
; #define PG8_MMA(ai, bj, At, Bt) do { __builtin_amdgcn_s_setprio(1); _Pragma("unroll") for (int m = 0; m < 4; ++m) _Pragma("unroll") for (int n = 0; n < 2; ++n) _Pragma("unroll") for (int k = 0; k < 2; ++k) \
;         acc[ai][bj][m][n] = __builtin_amdgcn_mfma_f32_16x16x32_bf16(Bt[n][k], At[m][k], acc[ai][bj][m][n], 0, 0, 0); __builtin_amdgcn_s_setprio(0); } while (0)
; #define PG8_WAIT_V(n) asm volatile("s_waitcnt vmcnt(" #n ")" ::: "memory")
; #define PG8_WAIT_L(n) asm volatile("s_waitcnt lgkmcnt(" #n ")" ::: "memory")
; #define PG8_BAR __builtin_amdgcn_s_barrier()
; #define PG8_SCHED __builtin_amdgcn_sched_barrier(0)
; template <class Epi, class Sched, bool ALIGN_EPI = false, bool SP2 = false>
; __device__ __forceinline__ void gemm_phase(PG8_LAS unsigned char* lds, const Gemm g, const Sched& S, const Epi& E, int wid_in) {
;     ...
;             PG8_WAIT_V(8); PG8_WAIT_L(0); PG8_BAR; PG8_MMA(1, 0, At, B0); PG8_MMA(1, 1, At, B1); PG8_BAR; PG8_SCHED;
;             PG8_LDB(B0, 1, 0); PG8_LDB(B1, 1, 1); PG8_SCHED; PG8_LDA(At, 1, 0); PG8_STAGE(PG8_SA(0, 1), a2 + hstep, voffA);
;             PG8_WAIT_V(8); PG8_WAIT_L(0); PG8_BAR; PG8_MMA(0, 0, At, B0); PG8_MMA(0, 1, At, B1); PG8_BAR; PG8_SCHED;
.Lp6t_w2a:
	s_waitcnt vmcnt(9)
.Lp6t_w2b:
	s_waitcnt lgkmcnt(0)
	s_barrier
	s_setprio 1
	s_waitcnt lgkmcnt(0)
	v_mfma_f32_16x16x32_bf16 v[60:63], v[156:159], v[188:191], v[60:63]
	v_mfma_f32_16x16x32_bf16 v[56:59], v[164:167], v[188:191], v[56:59]
	v_mfma_f32_16x16x32_bf16 v[88:91], v[156:159], v[196:199], v[88:91]
	v_mfma_f32_16x16x32_bf16 v[84:87], v[164:167], v[196:199], v[84:87]
	v_mfma_f32_16x16x32_bf16 v[108:111], v[156:159], v[204:207], v[108:111]
	v_mfma_f32_16x16x32_bf16 v[104:107], v[164:167], v[204:207], v[104:107]
	v_mfma_f32_16x16x32_bf16 v[124:127], v[156:159], v[212:215], v[124:127]
	v_mfma_f32_16x16x32_bf16 v[120:123], v[164:167], v[212:215], v[120:123]
	v_mfma_f32_16x16x32_bf16 v[60:63], v[160:163], v[192:195], v[60:63]
	v_mfma_f32_16x16x32_bf16 v[56:59], v[168:171], v[192:195], v[56:59]
	v_mfma_f32_16x16x32_bf16 v[88:91], v[160:163], v[200:203], v[88:91]
	v_mfma_f32_16x16x32_bf16 v[84:87], v[168:171], v[200:203], v[84:87]
	v_mfma_f32_16x16x32_bf16 v[108:111], v[160:163], v[208:211], v[108:111]
	v_mfma_f32_16x16x32_bf16 v[104:107], v[168:171], v[208:211], v[104:107]
	v_mfma_f32_16x16x32_bf16 v[124:127], v[160:163], v[216:219], v[124:127]
	v_mfma_f32_16x16x32_bf16 v[120:123], v[168:171], v[216:219], v[120:123]
	s_setprio 0
	s_setprio 1
	v_mfma_f32_16x16x32_bf16 v[36:39], v[172:175], v[188:191], v[36:39]
	v_mfma_f32_16x16x32_bf16 v[32:35], v[180:183], v[188:191], v[32:35]
	v_mfma_f32_16x16x32_bf16 v[68:71], v[172:175], v[196:199], v[68:71]
	v_mfma_f32_16x16x32_bf16 v[64:67], v[180:183], v[196:199], v[64:67]
	v_mfma_f32_16x16x32_bf16 v[100:103], v[172:175], v[204:207], v[100:103]
	v_mfma_f32_16x16x32_bf16 v[96:99], v[180:183], v[204:207], v[96:99]
	v_mfma_f32_16x16x32_bf16 v[116:119], v[172:175], v[212:215], v[116:119]
	v_mfma_f32_16x16x32_bf16 v[112:115], v[180:183], v[212:215], v[112:115]
	v_mfma_f32_16x16x32_bf16 v[36:39], v[176:179], v[192:195], v[36:39]
	v_mfma_f32_16x16x32_bf16 v[32:35], v[184:187], v[192:195], v[32:35]
	v_mfma_f32_16x16x32_bf16 v[68:71], v[176:179], v[200:203], v[68:71]
	v_mfma_f32_16x16x32_bf16 v[64:67], v[184:187], v[200:203], v[64:67]
	v_mfma_f32_16x16x32_bf16 v[100:103], v[176:179], v[208:211], v[100:103]
	v_mfma_f32_16x16x32_bf16 v[96:99], v[184:187], v[208:211], v[96:99]
	v_mfma_f32_16x16x32_bf16 v[116:119], v[176:179], v[216:219], v[116:119]
	v_mfma_f32_16x16x32_bf16 v[112:115], v[184:187], v[216:219], v[112:115]
	s_setprio 0
	s_barrier
	s_add_i32 s30, s49, s35
	v_lshl_add_u64 v[220:221], v[220:221], 0, s[14:15]
	s_mov_b32 m0, s30
	ds_read_b128 v[188:191], v154 offset:49152
	ds_read_b128 v[192:195], v154 offset:50176
	ds_read_b128 v[196:199], v154 offset:51200
	ds_read_b128 v[200:203], v154 offset:52224
	ds_read_b128 v[204:207], v154 offset:53248
	ds_read_b128 v[208:211], v154 offset:54272
	ds_read_b128 v[212:215], v154 offset:55296
	ds_read_b128 v[216:219], v154 offset:56320
	s_cmpk_eq_i32 s26, 0x700
	s_cbranch_scc1 .Lp6t_s3
	global_load_lds_dwordx4 v[220:221], off
	s_add_i32 m0, s30, 0x2000
	s_add_u32 s28, s28, 0x40080
	v_lshl_add_u64 v[220:221], v[222:223], 0, s[14:15]
	s_addc_u32 s29, s29, 0
	s_add_i32 s30, s50, s35
	global_load_lds_dwordx4 v[220:221], off
	v_lshl_add_u64 v[220:221], s[28:29], 0, v[130:131]
	s_mov_b32 m0, s30
	s_nop 0
	global_load_lds_dwordx4 v[220:221], off
	v_lshl_add_u64 v[220:221], s[28:29], 0, v[134:135]
	s_add_i32 m0, s30, 0x2000
	s_nop 0
	global_load_lds_dwordx4 v[220:221], off
	v_lshl_add_u64 v[220:221], v[224:225], 0, s[14:15]
	s_mov_b32 m0, s41
	s_nop 0
	global_load_lds_dwordx4 v[220:221], off
	v_lshl_add_u64 v[220:221], v[226:227], 0, s[14:15]
	s_mov_b32 m0, s42
	s_nop 0
	global_load_lds_dwordx4 v[220:221], off

; #define PG8_STAGE(bufoff, gbase, voff) do { _Pragma("unroll") for (int _i = 0; _i < 2; ++_i) \
;         __builtin_amdgcn_global_load_lds((const unsigned*)((const char*)(gbase) + (voff)[_i]), (PG8_LAS unsigned*)(lds + (bufoff) + ldsw + _i * 8192), 16, 0, 0); } while (0)
; #define PG8_LDA(dst, b, h) do { _Pragma("unroll") for (int m = 0; m < 4; ++m) _Pragma("unroll") for (int k = 0; k < 2; ++k) dst[m][k] = *(const PG8_LAS bf16x8*)(lds + PG8_SA(b, h) + aoff + m * 2048 + k * 1024); } while (0)
; #define PG8_MMA(ai, bj, At, Bt) do { __builtin_amdgcn_s_setprio(1); _Pragma("unroll") for (int m = 0; m < 4; ++m) _Pragma("unroll") for (int n = 0; n < 2; ++n) _Pragma("unroll") for (int k = 0; k < 2; ++k) \
;         acc[ai][bj][m][n] = __builtin_amdgcn_mfma_f32_16x16x32_bf16(Bt[n][k], At[m][k], acc[ai][bj][m][n], 0, 0, 0); __builtin_amdgcn_s_setprio(0); } while (0)
; #define PG8_WAIT_V(n) asm volatile("s_waitcnt vmcnt(" #n ")" ::: "memory")
; #define PG8_WAIT_L(n) asm volatile("s_waitcnt lgkmcnt(" #n ")" ::: "memory")
; #define PG8_BAR __builtin_amdgcn_s_barrier()
; #define PG8_SCHED __builtin_amdgcn_sched_barrier(0)
; template <class Epi, class Sched, bool ALIGN_EPI = false, bool SP2 = false>
; __device__ __forceinline__ void gemm_phase(PG8_LAS unsigned char* lds, const Gemm g, const Sched& S, const Epi& E, int wid_in) {
;     ...
;             PG8_LDA(At, 1, 1); PG8_STAGE(PG8_SB(1, 0), b3, voffB); PG8_STAGE(PG8_SB(1, 1), b3 + hstep, voffB); PG8_STAGE(PG8_SA(1, 0), a3, voffA);
;             PG8_WAIT_V(8); PG8_WAIT_L(0); PG8_BAR; PG8_MMA(1, 0, At, B0); PG8_MMA(1, 1, At, B1); PG8_BAR; PG8_SCHED;
;     ...
;         if (!has_next) break;
; #pragma unroll
;         for (int a = 0; a < 2; ++a)
; #pragma unroll
;             for (int b = 0; b < 2; ++b)
; #pragma unroll
;                 for (int m = 0; m < 4; ++m)
; #pragma unroll
;                     for (int n = 0; n < 2; ++n) acc[a][b][m][n] = (f32x4){0.f, 0.f, 0.f, 0.f};
.Lp6t_w3b:
	s_waitcnt lgkmcnt(0)
	s_barrier
	s_setprio 1
	s_waitcnt lgkmcnt(0)
	v_mfma_f32_16x16x32_bf16 v[92:95], v[156:159], v[188:191], v[92:95]
	v_mfma_f32_16x16x32_bf16 v[80:83], v[164:167], v[188:191], v[80:83]
	v_mfma_f32_16x16x32_bf16 v[52:55], v[156:159], v[196:199], v[52:55]
	v_mfma_f32_16x16x32_bf16 v[48:51], v[164:167], v[196:199], v[48:51]
	v_mfma_f32_16x16x32_bf16 v[28:31], v[156:159], v[204:207], v[28:31]
	v_mfma_f32_16x16x32_bf16 v[24:27], v[164:167], v[204:207], v[24:27]
	v_mfma_f32_16x16x32_bf16 v[12:15], v[156:159], v[212:215], v[12:15]
	v_mfma_f32_16x16x32_bf16 v[8:11], v[164:167], v[212:215], v[8:11]
	v_mfma_f32_16x16x32_bf16 v[92:95], v[160:163], v[192:195], v[92:95]
	v_mfma_f32_16x16x32_bf16 v[80:83], v[168:171], v[192:195], v[80:83]
	v_mfma_f32_16x16x32_bf16 v[52:55], v[160:163], v[200:203], v[52:55]
	v_mfma_f32_16x16x32_bf16 v[48:51], v[168:171], v[200:203], v[48:51]
	v_mfma_f32_16x16x32_bf16 v[28:31], v[160:163], v[208:211], v[28:31]
	v_mfma_f32_16x16x32_bf16 v[24:27], v[168:171], v[208:211], v[24:27]
	v_mfma_f32_16x16x32_bf16 v[12:15], v[160:163], v[216:219], v[12:15]
	v_mfma_f32_16x16x32_bf16 v[8:11], v[168:171], v[216:219], v[8:11]
	s_setprio 0
	s_setprio 1
	v_mfma_f32_16x16x32_bf16 v[76:79], v[172:175], v[188:191], v[76:79]
	v_mfma_f32_16x16x32_bf16 v[72:75], v[180:183], v[188:191], v[72:75]
	v_mfma_f32_16x16x32_bf16 v[44:47], v[172:175], v[196:199], v[44:47]
	v_mfma_f32_16x16x32_bf16 v[40:43], v[180:183], v[196:199], v[40:43]
	v_mfma_f32_16x16x32_bf16 v[20:23], v[172:175], v[204:207], v[20:23]
	v_mfma_f32_16x16x32_bf16 v[16:19], v[180:183], v[204:207], v[16:19]
	v_mfma_f32_16x16x32_bf16 v[4:7], v[172:175], v[212:215], v[4:7]
	v_mfma_f32_16x16x32_bf16 v[0:3], v[180:183], v[212:215], v[0:3]
	v_mfma_f32_16x16x32_bf16 v[76:79], v[176:179], v[192:195], v[76:79]
	v_mfma_f32_16x16x32_bf16 v[72:75], v[184:187], v[192:195], v[72:75]
	v_mfma_f32_16x16x32_bf16 v[44:47], v[176:179], v[200:203], v[44:47]
	v_mfma_f32_16x16x32_bf16 v[40:43], v[184:187], v[200:203], v[40:43]
	v_mfma_f32_16x16x32_bf16 v[20:23], v[176:179], v[208:211], v[20:23]
	v_mfma_f32_16x16x32_bf16 v[16:19], v[184:187], v[208:211], v[16:19]
	v_mfma_f32_16x16x32_bf16 v[4:7], v[176:179], v[216:219], v[4:7]
	v_mfma_f32_16x16x32_bf16 v[0:3], v[184:187], v[216:219], v[0:3]
	s_setprio 0
	s_barrier
	s_add_i32 s48, s48, 2
	s_add_u32 s26, s26, 0x100
	s_addc_u32 s27, s27, 0
	s_cmp_gt_u32 s48, 13
	s_cbranch_scc0 .LBB0_986
	s_add_u32 s26, s23, 0xffffff00
	s_addc_u32 s27, s45, -1
	s_andn2_b64 vcc, exec, s[2:3]
	s_cbranch_vccnz .LBB0_977
	v_mov_b32_e32 v0, 0
	s_mov_b32 s6, s16
	s_mov_b32 s4, s18
	s_mov_b64 s[10:11], s[24:25]
	s_mov_b32 s40, s22
	v_mov_b32_e32 v1, v0
	v_mov_b32_e32 v2, v0
	v_mov_b32_e32 v3, v0
	v_mov_b32_e32 v4, v0
	v_mov_b32_e32 v5, v0
	v_mov_b32_e32 v6, v0
	v_mov_b32_e32 v7, v0
	v_mov_b32_e32 v16, v0
	v_mov_b32_e32 v17, v0
	v_mov_b32_e32 v18, v0
	v_mov_b32_e32 v19, v0
	v_mov_b32_e32 v20, v0
	v_mov_b32_e32 v21, v0
	v_mov_b32_e32 v22, v0
	v_mov_b32_e32 v23, v0
	v_mov_b32_e32 v40, v0
	v_mov_b32_e32 v41, v0
	v_mov_b32_e32 v42, v0
	v_mov_b32_e32 v43, v0
	v_mov_b32_e32 v44, v0
	v_mov_b32_e32 v45, v0
	v_mov_b32_e32 v46, v0
	v_mov_b32_e32 v47, v0
	v_mov_b32_e32 v72, v0
	v_mov_b32_e32 v73, v0
	v_mov_b32_e32 v74, v0
	v_mov_b32_e32 v75, v0
	v_mov_b32_e32 v76, v0
	v_mov_b32_e32 v77, v0
	v_mov_b32_e32 v78, v0
	v_mov_b32_e32 v79, v0
	v_mov_b32_e32 v8, v0
	v_mov_b32_e32 v9, v0
	v_mov_b32_e32 v10, v0
	v_mov_b32_e32 v11, v0
	v_mov_b32_e32 v12, v0
	v_mov_b32_e32 v13, v0
	v_mov_b32_e32 v14, v0
	v_mov_b32_e32 v15, v0
	v_mov_b32_e32 v24, v0
	v_mov_b32_e32 v25, v0
	v_mov_b32_e32 v26, v0
	v_mov_b32_e32 v27, v0
	v_mov_b32_e32 v28, v0
	v_mov_b32_e32 v29, v0
	v_mov_b32_e32 v30, v0
	v_mov_b32_e32 v31, v0
	v_mov_b32_e32 v48, v0
	v_mov_b32_e32 v49, v0
	v_mov_b32_e32 v50, v0
	v_mov_b32_e32 v51, v0
	v_mov_b32_e32 v52, v0
	v_mov_b32_e32 v53, v0
	v_mov_b32_e32 v54, v0
	v_mov_b32_e32 v55, v0
	v_mov_b32_e32 v80, v0
	v_mov_b32_e32 v81, v0
	v_mov_b32_e32 v82, v0
	v_mov_b32_e32 v83, v0
	v_mov_b32_e32 v92, v0
	v_mov_b32_e32 v93, v0
	v_mov_b32_e32 v94, v0
	v_mov_b32_e32 v95, v0
	v_mov_b32_e32 v112, v0
	v_mov_b32_e32 v113, v0
	v_mov_b32_e32 v114, v0
	v_mov_b32_e32 v115, v0
	v_mov_b32_e32 v116, v0
	v_mov_b32_e32 v117, v0
	v_mov_b32_e32 v118, v0
	v_mov_b32_e32 v119, v0
	v_mov_b32_e32 v96, v0
	v_mov_b32_e32 v97, v0
	v_mov_b32_e32 v98, v0
	v_mov_b32_e32 v99, v0
	v_mov_b32_e32 v100, v0
	v_mov_b32_e32 v101, v0
	v_mov_b32_e32 v102, v0
	v_mov_b32_e32 v103, v0
	v_mov_b32_e32 v64, v0
	v_mov_b32_e32 v65, v0
	v_mov_b32_e32 v66, v0
	v_mov_b32_e32 v67, v0
	v_mov_b32_e32 v68, v0
	v_mov_b32_e32 v69, v0
	v_mov_b32_e32 v70, v0
	v_mov_b32_e32 v71, v0
	v_mov_b32_e32 v32, v0
	v_mov_b32_e32 v33, v0
	v_mov_b32_e32 v34, v0
	v_mov_b32_e32 v35, v0
	v_mov_b32_e32 v36, v0
	v_mov_b32_e32 v37, v0
	v_mov_b32_e32 v38, v0
	v_mov_b32_e32 v39, v0
	v_mov_b32_e32 v120, v0
	v_mov_b32_e32 v121, v0
	v_mov_b32_e32 v122, v0
	v_mov_b32_e32 v123, v0
	v_mov_b32_e32 v124, v0
	v_mov_b32_e32 v125, v0
	v_mov_b32_e32 v126, v0
	v_mov_b32_e32 v127, v0
	v_mov_b32_e32 v104, v0
	v_mov_b32_e32 v105, v0
	v_mov_b32_e32 v106, v0
	v_mov_b32_e32 v107, v0
	v_mov_b32_e32 v108, v0
	v_mov_b32_e32 v109, v0
	v_mov_b32_e32 v110, v0
	v_mov_b32_e32 v111, v0
	v_mov_b32_e32 v84, v0
	v_mov_b32_e32 v85, v0
	v_mov_b32_e32 v86, v0
	v_mov_b32_e32 v87, v0
	v_mov_b32_e32 v88, v0
	v_mov_b32_e32 v89, v0
	v_mov_b32_e32 v90, v0
	v_mov_b32_e32 v91, v0
	v_mov_b32_e32 v56, v0
	v_mov_b32_e32 v57, v0
	v_mov_b32_e32 v58, v0
	v_mov_b32_e32 v59, v0
	v_mov_b32_e32 v60, v0
	v_mov_b32_e32 v61, v0
	v_mov_b32_e32 v62, v0
	v_mov_b32_e32 v63, v0
	s_andn2_b64 vcc, exec, s[0:1]
	s_cbranch_vccnz .LBB0_978

;     __device__ __forceinline__ void fused(f32x4 (&acc)[2][2][4][2], const Unit& u, int wr, int wc, int fr, int fq, PG8_LAS unsigned char* lds, int wid, int lane) const {
;     ...
; #pragma unroll
;         for (int bj = 0; bj < 2; ++bj) {
;             const f32x4 b0 = *(const f32x4*)(gb + col0 + bj * HALF), b1 = *(const f32x4*)(gb + col0 + bj * HALF + 4);
; #pragma unroll
;             for (int ai = 0; ai < 2; ++ai)
; #pragma unroll
;                 for (int m = 0; m < 4; ++m) { acc[ai][bj][m][0] += b0; acc[ai][bj][m][1] += b1; } }
; #pragma unroll
;         for (int ai = 0; ai < 2; ++ai)
; #pragma unroll
;             for (int m = 0; m < 4; ++m) { const size_t off = (size_t)(u.pm * BM + ai * HALF + wr * 64 + m * 16 + fr) * 1024 + col0;
; #pragma unroll
;                 for (int bj = 0; bj < 2; ++bj) {
;                     const u32x4 xw = *(const u32x4*)(x1b + off + bj * HALF);
;                     f32x4 x0, x1;
;                     x0[0] = __uint_as_float(xw.x << 16); x0[1] = __uint_as_float(xw.x & 0xffff0000u); x0[2] = __uint_as_float(xw.y << 16); x0[3] = __uint_as_float(xw.y & 0xffff0000u);
;                     x1[0] = __uint_as_float(xw.z << 16); x1[1] = __uint_as_float(xw.z & 0xffff0000u); x1[2] = __uint_as_float(xw.w << 16); x1[3] = __uint_as_float(xw.w & 0xffff0000u);
;                     const u32x4 pw = *(const u32x4*)(pp + off + bj * HALF);
;                     f32x4 p0, p1;
;                     p0[0] = __uint_as_float(pw.x << 16); p0[1] = __uint_as_float(pw.x & 0xffff0000u); p0[2] = __uint_as_float(pw.y << 16); p0[3] = __uint_as_float(pw.y & 0xffff0000u);
;                     p1[0] = __uint_as_float(pw.z << 16); p1[1] = __uint_as_float(pw.z & 0xffff0000u); p1[2] = __uint_as_float(pw.w << 16); p1[3] = __uint_as_float(pw.w & 0xffff0000u);
;                     f32x4 g0 = acc[ai][bj][m][0], g1 = acc[ai][bj][m][1];
; #pragma unroll
;                     for (int e = 0; e < 4; ++e) { g0[e] = __builtin_amdgcn_rcpf(1.f + __expf(-g0[e])); g1[e] = __builtin_amdgcn_rcpf(1.f + __expf(-g1[e])); }
;                     acc[ai][bj][m][0] = x0 + g0 * p0; acc[ai][bj][m][1] = x1 + g1 * p1; }
.LBB0_991:
	v_mov_b32_e32 v160, v136
	v_mov_b32_e32 v161, v137
	v_mov_b32_e32 v162, v138
	v_mov_b32_e32 v163, v139
	v_mov_b32_e32 v164, v140
	v_mov_b32_e32 v165, v141
	v_mov_b32_e32 v166, v142
	v_mov_b32_e32 v167, v143
	s_add_u32 s0, s96, 0xdc00000
	s_addc_u32 s1, s97, 0
	v_ashrrev_i32_e32 v128, 1, v150
	s_lshl_b32 s2, s5, 5
	s_lshl_b32 s3, s6, 8
	v_and_b32_e32 v130, -8, v128
	s_or_b32 s2, s3, s2
	v_add_u32_e32 v144, s2, v130
	v_ashrrev_i32_e32 v145, 31, v144
	s_barrier
	v_mov_b32_e32 v132, v230
	v_mov_b32_e32 v133, v231
	v_mov_b32_e32 v134, v232
	v_mov_b32_e32 v135, v233
	v_mov_b32_e32 v128, v234
	v_mov_b32_e32 v129, v235
	v_mov_b32_e32 v130, v236
	v_mov_b32_e32 v131, v237
	v_mov_b32_e32 v140, v238
	v_mov_b32_e32 v141, v239
	v_mov_b32_e32 v142, v240
	v_mov_b32_e32 v143, v241
	v_mov_b32_e32 v136, v242
	v_mov_b32_e32 v137, v243
	v_mov_b32_e32 v138, v244
	v_mov_b32_e32 v139, v245
	s_lshl_b32 s16, s4, 8
	s_add_i32 s2, s16, s12
	v_or_b32_e32 v146, s2, v152
	v_ashrrev_i32_e32 v147, 31, v146
	v_mov_b32_e32 v152, v246
	v_mov_b32_e32 v153, v247
	v_mov_b32_e32 v154, v248
	v_mov_b32_e32 v155, v249
	v_mov_b32_e32 v156, v250
	v_mov_b32_e32 v157, v251
	v_mov_b32_e32 v158, v254
	v_mov_b32_e32 v159, v255
	s_waitcnt vmcnt(0)
	v_pk_add_f32 v[60:61], v[60:61], v[132:133]
	v_pk_add_f32 v[56:57], v[56:57], v[128:129]
	v_mul_f32_e32 v60, 0xbfb8aa3b, v60
	v_mul_f32_e32 v56, 0xbfb8aa3b, v56
	v_exp_f32_e32 v147, v60
	v_exp_f32_e32 v172, v56
	v_pk_add_f32 v[36:37], v[36:37], v[140:141]
	v_pk_add_f32 v[32:33], v[32:33], v[136:137]
	v_add_f32_e32 v147, 1.0, v147
	v_mul_f32_e32 v36, 0xbfb8aa3b, v36
	v_mul_f32_e32 v32, 0xbfb8aa3b, v32
	v_add_f32_e32 v179, 1.0, v172
	v_rcp_f32_e32 v172, v147
	v_exp_f32_e32 v36, v36
	v_exp_f32_e32 v147, v32
	v_mul_f32_e32 v37, 0xbfb8aa3b, v37
	v_mul_f32_e32 v33, 0xbfb8aa3b, v33
	v_add_f32_e32 v32, 1.0, v36
	v_add_f32_e32 v36, 1.0, v147
	v_exp_f32_e32 v37, v37
	v_exp_f32_e32 v147, v33
	v_mul_f32_e32 v61, 0xbfb8aa3b, v61
	v_pk_add_f32 v[38:39], v[38:39], v[142:143]
	v_pk_add_f32 v[34:35], v[34:35], v[138:139]
	v_exp_f32_e32 v173, v61
	v_mul_f32_e32 v38, 0xbfb8aa3b, v38
	v_mul_f32_e32 v34, 0xbfb8aa3b, v34
	v_add_f32_e32 v33, 1.0, v37
	v_add_f32_e32 v37, 1.0, v147
	v_exp_f32_e32 v38, v38
	v_exp_f32_e32 v147, v34
	v_pk_add_f32 v[62:63], v[62:63], v[134:135]
	v_pk_add_f32 v[58:59], v[58:59], v[130:131]
	v_mul_f32_e32 v57, 0xbfb8aa3b, v57
	v_mul_f32_e32 v62, 0xbfb8aa3b, v62
	v_mul_f32_e32 v58, 0xbfb8aa3b, v58
	v_mul_f32_e32 v63, 0xbfb8aa3b, v63
	v_mul_f32_e32 v59, 0xbfb8aa3b, v59
	v_exp_f32_e32 v174, v57
	v_add_f32_e32 v173, 1.0, v173
	v_exp_f32_e32 v175, v62
	v_exp_f32_e32 v176, v58
	v_exp_f32_e32 v177, v63
	v_exp_f32_e32 v178, v59
	v_rcp_f32_e32 v173, v173
	v_mul_f32_e32 v39, 0xbfb8aa3b, v39
	v_mul_f32_e32 v35, 0xbfb8aa3b, v35
	v_rcp_f32_e32 v32, v32
	v_rcp_f32_e32 v33, v33
	v_add_f32_e32 v34, 1.0, v38
	v_add_f32_e32 v38, 1.0, v147
	v_exp_f32_e32 v39, v39
	v_exp_f32_e32 v147, v35
	v_lshlrev_b32_e32 v56, 16, v152
	v_and_b32_e32 v57, 0xffff0000, v152
	v_lshlrev_b32_e32 v58, 16, v153
	v_and_b32_e32 v59, 0xffff0000, v153
	v_lshlrev_b32_e32 v152, 16, v156
	v_and_b32_e32 v153, 0xffff0000, v156
	v_add_f32_e32 v180, 1.0, v174
	v_lshlrev_b32_e32 v168, 16, v160
	v_and_b32_e32 v169, 0xffff0000, v160
	v_add_f32_e32 v181, 1.0, v175
	v_add_f32_e32 v182, 1.0, v176
	v_add_f32_e32 v177, 1.0, v177
	v_add_f32_e32 v183, 1.0, v178
	v_rcp_f32_e32 v174, v179
	v_rcp_f32_e32 v175, v180
	v_pk_fma_f32 v[56:57], v[172:173], v[152:153], v[56:57]
	v_lshlrev_b32_e32 v152, 16, v164
	v_and_b32_e32 v153, 0xffff0000, v164
	v_rcp_f32_e32 v176, v181
	v_rcp_f32_e32 v177, v177
	v_rcp_f32_e32 v178, v182
	v_rcp_f32_e32 v179, v183
	v_rcp_f32_e32 v36, v36
	v_rcp_f32_e32 v37, v37
	v_add_f32_e32 v35, 1.0, v39
	v_add_f32_e32 v39, 1.0, v147
	v_pk_fma_f32 v[32:33], v[32:33], v[152:153], v[168:169]
	v_or_b32_e32 v152, 16, v146
	v_rcp_f32_e32 v34, v34
	v_rcp_f32_e32 v38, v38
	v_rcp_f32_e32 v35, v35
	v_rcp_f32_e32 v39, v39
	v_ashrrev_i32_e32 v153, 31, v152
	v_lshlrev_b32_e32 v60, 16, v154
	v_and_b32_e32 v61, 0xffff0000, v154
	v_lshlrev_b32_e32 v62, 16, v155
	v_and_b32_e32 v63, 0xffff0000, v155
	v_lshlrev_b32_e32 v154, 16, v157
	v_and_b32_e32 v155, 0xffff0000, v157
	v_lshlrev_b32_e32 v156, 16, v158
	v_and_b32_e32 v157, 0xffff0000, v158
	v_lshlrev_b64 v[152:153], 10, v[152:153]
	v_lshlrev_b32_e32 v158, 16, v159
	v_and_b32_e32 v159, 0xffff0000, v159
	v_lshlrev_b32_e32 v170, 16, v162
	v_and_b32_e32 v171, 0xffff0000, v162
	v_pk_fma_f32 v[60:61], v[174:175], v[156:157], v[60:61]
	v_lshlrev_b32_e32 v156, 16, v166
	v_and_b32_e32 v157, 0xffff0000, v166
	v_lshl_add_u64 v[152:153], v[152:153], 0, v[144:145]
	v_lshlrev_b32_e32 v160, 16, v161
	v_and_b32_e32 v161, 0xffff0000, v161
	v_lshlrev_b32_e32 v162, 16, v163
	v_and_b32_e32 v163, 0xffff0000, v163
	v_pk_fma_f32 v[58:59], v[176:177], v[154:155], v[58:59]
	v_pk_fma_f32 v[62:63], v[178:179], v[158:159], v[62:63]
	v_lshlrev_b32_e32 v154, 16, v165
	v_and_b32_e32 v155, 0xffff0000, v165
	v_lshlrev_b32_e32 v158, 16, v167
	v_and_b32_e32 v159, 0xffff0000, v167
	v_pk_fma_f32 v[36:37], v[36:37], v[156:157], v[170:171]
	v_lshlrev_b64 v[156:157], 1, v[152:153]
	v_pk_fma_f32 v[34:35], v[34:35], v[154:155], v[160:161]
	v_pk_fma_f32 v[38:39], v[38:39], v[158:159], v[162:163]
	v_lshl_add_u64 v[160:161], s[8:9], 0, v[156:157]
	global_load_dwordx4 v[152:155], v[160:161], off
	v_lshl_add_u64 v[164:165], s[0:1], 0, v[156:157]
	global_load_dwordx4 v[156:159], v[164:165], off
	s_nop 0
	global_load_dwordx4 v[160:163], v[160:161], off offset:256
	s_nop 0
	global_load_dwordx4 v[164:167], v[164:165], off offset:256
	v_pk_add_f32 v[88:89], v[88:89], v[132:133]
;     __device__ __forceinline__ void fused(f32x4 (&acc)[2][2][4][2], const Unit& u, int wr, int wc, int fr, int fq, PG8_LAS unsigned char* lds, int wid, int lane) const {
;     ...
;         for (int ai = 0; ai < 2; ++ai)
; #pragma unroll
;             for (int m = 0; m < 4; ++m) { const size_t off = (size_t)(u.pm * BM + ai * HALF + wr * 64 + m * 16 + fr) * 1024 + col0;
; #pragma unroll
;                 for (int bj = 0; bj < 2; ++bj) {
;                     const u32x4 xw = *(const u32x4*)(x1b + off + bj * HALF);
;                     f32x4 x0, x1;
;                     x0[0] = __uint_as_float(xw.x << 16); x0[1] = __uint_as_float(xw.x & 0xffff0000u); x0[2] = __uint_as_float(xw.y << 16); x0[3] = __uint_as_float(xw.y & 0xffff0000u);
;                     x1[0] = __uint_as_float(xw.z << 16); x1[1] = __uint_as_float(xw.z & 0xffff0000u); x1[2] = __uint_as_float(xw.w << 16); x1[3] = __uint_as_float(xw.w & 0xffff0000u);
;                     const u32x4 pw = *(const u32x4*)(pp + off + bj * HALF);
;                     f32x4 p0, p1;
;                     p0[0] = __uint_as_float(pw.x << 16); p0[1] = __uint_as_float(pw.x & 0xffff0000u); p0[2] = __uint_as_float(pw.y << 16); p0[3] = __uint_as_float(pw.y & 0xffff0000u);
;                     p1[0] = __uint_as_float(pw.z << 16); p1[1] = __uint_as_float(pw.z & 0xffff0000u); p1[2] = __uint_as_float(pw.w << 16); p1[3] = __uint_as_float(pw.w & 0xffff0000u);
;                     f32x4 g0 = acc[ai][bj][m][0], g1 = acc[ai][bj][m][1];
; #pragma unroll
;                     for (int e = 0; e < 4; ++e) { g0[e] = __builtin_amdgcn_rcpf(1.f + __expf(-g0[e])); g1[e] = __builtin_amdgcn_rcpf(1.f + __expf(-g1[e])); }
;                     acc[ai][bj][m][0] = x0 + g0 * p0; acc[ai][bj][m][1] = x1 + g1 * p1; }
	v_pk_add_f32 v[84:85], v[84:85], v[128:129]
	v_mul_f32_e32 v88, 0xbfb8aa3b, v88
	v_mul_f32_e32 v84, 0xbfb8aa3b, v84
	v_exp_f32_e32 v88, v88
	v_exp_f32_e32 v147, v84
	v_mul_f32_e32 v89, 0xbfb8aa3b, v89
	v_mul_f32_e32 v85, 0xbfb8aa3b, v85
	v_add_f32_e32 v84, 1.0, v88
	v_add_f32_e32 v88, 1.0, v147
	v_exp_f32_e32 v89, v89
	v_exp_f32_e32 v147, v85
	v_pk_add_f32 v[90:91], v[90:91], v[134:135]
	v_pk_add_f32 v[86:87], v[86:87], v[130:131]
	v_mul_f32_e32 v90, 0xbfb8aa3b, v90
	v_mul_f32_e32 v86, 0xbfb8aa3b, v86
	v_add_f32_e32 v85, 1.0, v89
	v_add_f32_e32 v89, 1.0, v147
	v_exp_f32_e32 v90, v90
	v_exp_f32_e32 v147, v86
	v_mul_f32_e32 v91, 0xbfb8aa3b, v91
	v_mul_f32_e32 v87, 0xbfb8aa3b, v87
	v_add_f32_e32 v86, 1.0, v90
	v_add_f32_e32 v90, 1.0, v147
	v_exp_f32_e32 v91, v91
	v_exp_f32_e32 v147, v87
	v_pk_add_f32 v[68:69], v[68:69], v[140:141]
	v_pk_add_f32 v[64:65], v[64:65], v[136:137]
	v_mul_f32_e32 v68, 0xbfb8aa3b, v68
	v_mul_f32_e32 v64, 0xbfb8aa3b, v64
	v_add_f32_e32 v87, 1.0, v91
	v_add_f32_e32 v91, 1.0, v147
	v_exp_f32_e32 v68, v68
	v_exp_f32_e32 v147, v64
	v_mul_f32_e32 v69, 0xbfb8aa3b, v69
	v_mul_f32_e32 v65, 0xbfb8aa3b, v65
	v_add_f32_e32 v64, 1.0, v68
	v_add_f32_e32 v68, 1.0, v147
	v_exp_f32_e32 v69, v69
	v_exp_f32_e32 v147, v65
	v_pk_add_f32 v[70:71], v[70:71], v[142:143]
	v_pk_add_f32 v[66:67], v[66:67], v[138:139]
	v_mul_f32_e32 v70, 0xbfb8aa3b, v70
	v_mul_f32_e32 v66, 0xbfb8aa3b, v66
	v_add_f32_e32 v65, 1.0, v69
	v_add_f32_e32 v69, 1.0, v147
	v_exp_f32_e32 v70, v70
	v_exp_f32_e32 v147, v66
	v_rcp_f32_e32 v86, v86
	v_rcp_f32_e32 v90, v90
	v_rcp_f32_e32 v87, v87
	v_rcp_f32_e32 v91, v91
	v_mul_f32_e32 v71, 0xbfb8aa3b, v71
	v_mul_f32_e32 v67, 0xbfb8aa3b, v67
	v_rcp_f32_e32 v64, v64
	v_rcp_f32_e32 v65, v65
	v_add_f32_e32 v66, 1.0, v70
	v_add_f32_e32 v70, 1.0, v147
	v_exp_f32_e32 v71, v71
	v_exp_f32_e32 v147, v67
	v_rcp_f32_e32 v68, v68
	v_rcp_f32_e32 v69, v69
	v_add_f32_e32 v67, 1.0, v71
	v_add_f32_e32 v71, 1.0, v147
	v_rcp_f32_e32 v84, v84
	v_rcp_f32_e32 v88, v88
	v_rcp_f32_e32 v85, v85
	v_rcp_f32_e32 v89, v89
	v_rcp_f32_e32 v66, v66
	v_rcp_f32_e32 v70, v70
	v_rcp_f32_e32 v67, v67
	v_rcp_f32_e32 v71, v71
	v_pk_add_f32 v[108:109], v[108:109], v[132:133]
	v_pk_add_f32 v[104:105], v[104:105], v[128:129]
	v_mul_f32_e32 v108, 0xbfb8aa3b, v108
	v_mul_f32_e32 v104, 0xbfb8aa3b, v104
	v_exp_f32_e32 v108, v108
	s_waitcnt vmcnt(3)
	v_lshlrev_b32_e32 v168, 16, v152
	v_and_b32_e32 v169, 0xffff0000, v152
	v_lshlrev_b32_e32 v152, 16, v153
	v_and_b32_e32 v153, 0xffff0000, v153
	v_lshlrev_b32_e32 v170, 16, v154
	v_and_b32_e32 v171, 0xffff0000, v154
	v_lshlrev_b32_e32 v154, 16, v155
	v_and_b32_e32 v155, 0xffff0000, v155
	s_waitcnt vmcnt(2)
	v_lshlrev_b32_e32 v172, 16, v156
	v_and_b32_e32 v173, 0xffff0000, v156
	v_lshlrev_b32_e32 v156, 16, v157
	v_and_b32_e32 v157, 0xffff0000, v157
	v_lshlrev_b32_e32 v174, 16, v158
	v_and_b32_e32 v175, 0xffff0000, v158
	v_lshlrev_b32_e32 v158, 16, v159
	v_and_b32_e32 v159, 0xffff0000, v159
	v_pk_fma_f32 v[86:87], v[86:87], v[156:157], v[152:153]
	v_pk_fma_f32 v[90:91], v[90:91], v[158:159], v[154:155]
	s_waitcnt vmcnt(1)
	v_lshlrev_b32_e32 v152, 16, v160
	v_and_b32_e32 v153, 0xffff0000, v160
	v_lshlrev_b32_e32 v154, 16, v161
	v_and_b32_e32 v155, 0xffff0000, v161
	s_waitcnt vmcnt(0)
	v_lshlrev_b32_e32 v160, 16, v164
	v_and_b32_e32 v161, 0xffff0000, v164
	v_pk_fma_f32 v[64:65], v[64:65], v[160:161], v[152:153]
	v_or_b32_e32 v152, 32, v146
	v_ashrrev_i32_e32 v153, 31, v152
	v_lshlrev_b64 v[152:153], 10, v[152:153]
	v_lshlrev_b32_e32 v156, 16, v162
	v_and_b32_e32 v157, 0xffff0000, v162
	v_lshlrev_b32_e32 v158, 16, v163
	v_and_b32_e32 v159, 0xffff0000, v163
	v_lshlrev_b32_e32 v162, 16, v165
	v_and_b32_e32 v163, 0xffff0000, v165
	v_lshlrev_b32_e32 v164, 16, v166
	v_and_b32_e32 v165, 0xffff0000, v166
	v_lshl_add_u64 v[152:153], v[152:153], 0, v[144:145]
	v_lshlrev_b32_e32 v166, 16, v167
	v_and_b32_e32 v167, 0xffff0000, v167
	v_pk_fma_f32 v[68:69], v[68:69], v[164:165], v[156:157]
	v_lshlrev_b64 v[156:157], 1, v[152:153]
	v_pk_fma_f32 v[84:85], v[84:85], v[172:173], v[168:169]
	v_pk_fma_f32 v[88:89], v[88:89], v[174:175], v[170:171]
	v_pk_fma_f32 v[66:67], v[66:67], v[162:163], v[154:155]
	v_pk_fma_f32 v[70:71], v[70:71], v[166:167], v[158:159]
	v_lshl_add_u64 v[160:161], s[8:9], 0, v[156:157]
	global_load_dwordx4 v[152:155], v[160:161], off
	v_lshl_add_u64 v[164:165], s[0:1], 0, v[156:157]
	global_load_dwordx4 v[156:159], v[164:165], off
	s_nop 0
	global_load_dwordx4 v[160:163], v[160:161], off offset:256
	s_nop 0
	global_load_dwordx4 v[164:167], v[164:165], off offset:256
	v_exp_f32_e32 v147, v104
	v_mul_f32_e32 v109, 0xbfb8aa3b, v109
	v_mul_f32_e32 v105, 0xbfb8aa3b, v105
	v_add_f32_e32 v104, 1.0, v108
	v_add_f32_e32 v108, 1.0, v147
	v_exp_f32_e32 v109, v109
	v_exp_f32_e32 v147, v105
	v_pk_add_f32 v[110:111], v[110:111], v[134:135]
	v_pk_add_f32 v[106:107], v[106:107], v[130:131]
	v_mul_f32_e32 v110, 0xbfb8aa3b, v110
	v_mul_f32_e32 v106, 0xbfb8aa3b, v106
	v_add_f32_e32 v105, 1.0, v109
	v_add_f32_e32 v109, 1.0, v147
	v_exp_f32_e32 v110, v110
	v_exp_f32_e32 v147, v106
	v_mul_f32_e32 v111, 0xbfb8aa3b, v111
	v_mul_f32_e32 v107, 0xbfb8aa3b, v107
	v_add_f32_e32 v106, 1.0, v110
	v_add_f32_e32 v110, 1.0, v147
	v_exp_f32_e32 v111, v111
	v_exp_f32_e32 v147, v107
	v_pk_add_f32 v[100:101], v[100:101], v[140:141]
	v_pk_add_f32 v[96:97], v[96:97], v[136:137]
	v_mul_f32_e32 v100, 0xbfb8aa3b, v100
	v_mul_f32_e32 v96, 0xbfb8aa3b, v96
	v_add_f32_e32 v107, 1.0, v111
	v_add_f32_e32 v111, 1.0, v147
	v_exp_f32_e32 v100, v100
	v_exp_f32_e32 v147, v96
	v_mul_f32_e32 v101, 0xbfb8aa3b, v101
	v_mul_f32_e32 v97, 0xbfb8aa3b, v97
	v_add_f32_e32 v96, 1.0, v100
	v_add_f32_e32 v100, 1.0, v147
	v_exp_f32_e32 v101, v101
	v_exp_f32_e32 v147, v97
	v_pk_add_f32 v[102:103], v[102:103], v[142:143]
	v_pk_add_f32 v[98:99], v[98:99], v[138:139]
	v_mul_f32_e32 v102, 0xbfb8aa3b, v102
	v_mul_f32_e32 v98, 0xbfb8aa3b, v98
	v_add_f32_e32 v97, 1.0, v101
	v_add_f32_e32 v101, 1.0, v147
	v_exp_f32_e32 v102, v102
	v_exp_f32_e32 v147, v98
	v_rcp_f32_e32 v106, v106
	v_rcp_f32_e32 v110, v110
	v_rcp_f32_e32 v107, v107
	v_rcp_f32_e32 v111, v111
	v_mul_f32_e32 v103, 0xbfb8aa3b, v103
	v_mul_f32_e32 v99, 0xbfb8aa3b, v99
	v_rcp_f32_e32 v96, v96
	v_rcp_f32_e32 v97, v97
	v_add_f32_e32 v98, 1.0, v102
	v_add_f32_e32 v102, 1.0, v147
	v_exp_f32_e32 v103, v103
	v_exp_f32_e32 v147, v99
	v_rcp_f32_e32 v100, v100
	v_rcp_f32_e32 v101, v101
	v_add_f32_e32 v99, 1.0, v103
	v_add_f32_e32 v103, 1.0, v147
	v_rcp_f32_e32 v104, v104
	v_rcp_f32_e32 v108, v108
	v_rcp_f32_e32 v105, v105
	v_rcp_f32_e32 v109, v109
	v_rcp_f32_e32 v98, v98
	v_rcp_f32_e32 v102, v102
	v_rcp_f32_e32 v99, v99
	v_rcp_f32_e32 v103, v103
	v_pk_add_f32 v[124:125], v[124:125], v[132:133]
	v_pk_add_f32 v[120:121], v[120:121], v[128:129]
	v_mul_f32_e32 v124, 0xbfb8aa3b, v124
	v_mul_f32_e32 v120, 0xbfb8aa3b, v120
	v_exp_f32_e32 v124, v124
	v_exp_f32_e32 v147, v120
	v_mul_f32_e32 v121, 0xbfb8aa3b, v121
	v_mul_f32_e32 v125, 0xbfb8aa3b, v125
	v_add_f32_e32 v120, 1.0, v124
	v_add_f32_e32 v124, 1.0, v147
	s_waitcnt vmcnt(3)
;     __device__ __forceinline__ void fused(f32x4 (&acc)[2][2][4][2], const Unit& u, int wr, int wc, int fr, int fq, PG8_LAS unsigned char* lds, int wid, int lane) const {
;     ...
;         for (int ai = 0; ai < 2; ++ai)
; #pragma unroll
;             for (int m = 0; m < 4; ++m) { const size_t off = (size_t)(u.pm * BM + ai * HALF + wr * 64 + m * 16 + fr) * 1024 + col0;
; #pragma unroll
;                 for (int bj = 0; bj < 2; ++bj) {
;                     const u32x4 xw = *(const u32x4*)(x1b + off + bj * HALF);
;                     f32x4 x0, x1;
;                     x0[0] = __uint_as_float(xw.x << 16); x0[1] = __uint_as_float(xw.x & 0xffff0000u); x0[2] = __uint_as_float(xw.y << 16); x0[3] = __uint_as_float(xw.y & 0xffff0000u);
;                     x1[0] = __uint_as_float(xw.z << 16); x1[1] = __uint_as_float(xw.z & 0xffff0000u); x1[2] = __uint_as_float(xw.w << 16); x1[3] = __uint_as_float(xw.w & 0xffff0000u);
;                     const u32x4 pw = *(const u32x4*)(pp + off + bj * HALF);
;                     f32x4 p0, p1;
;                     p0[0] = __uint_as_float(pw.x << 16); p0[1] = __uint_as_float(pw.x & 0xffff0000u); p0[2] = __uint_as_float(pw.y << 16); p0[3] = __uint_as_float(pw.y & 0xffff0000u);
;                     p1[0] = __uint_as_float(pw.z << 16); p1[1] = __uint_as_float(pw.z & 0xffff0000u); p1[2] = __uint_as_float(pw.w << 16); p1[3] = __uint_as_float(pw.w & 0xffff0000u);
;                     f32x4 g0 = acc[ai][bj][m][0], g1 = acc[ai][bj][m][1];
; #pragma unroll
;                     for (int e = 0; e < 4; ++e) { g0[e] = __builtin_amdgcn_rcpf(1.f + __expf(-g0[e])); g1[e] = __builtin_amdgcn_rcpf(1.f + __expf(-g1[e])); }
;                     acc[ai][bj][m][0] = x0 + g0 * p0; acc[ai][bj][m][1] = x1 + g1 * p1; }
	v_lshlrev_b32_e32 v168, 16, v152
	v_and_b32_e32 v169, 0xffff0000, v152
	v_lshlrev_b32_e32 v152, 16, v153
	v_and_b32_e32 v153, 0xffff0000, v153
	v_lshlrev_b32_e32 v170, 16, v154
	v_and_b32_e32 v171, 0xffff0000, v154
	v_lshlrev_b32_e32 v154, 16, v155
	v_and_b32_e32 v155, 0xffff0000, v155
	s_waitcnt vmcnt(2)
	v_lshlrev_b32_e32 v172, 16, v156
	v_and_b32_e32 v173, 0xffff0000, v156
	v_lshlrev_b32_e32 v156, 16, v157
	v_and_b32_e32 v157, 0xffff0000, v157
	v_lshlrev_b32_e32 v174, 16, v158
	v_and_b32_e32 v175, 0xffff0000, v158
	v_lshlrev_b32_e32 v158, 16, v159
	v_and_b32_e32 v159, 0xffff0000, v159
	v_pk_fma_f32 v[106:107], v[106:107], v[156:157], v[152:153]
	v_pk_fma_f32 v[110:111], v[110:111], v[158:159], v[154:155]
	s_waitcnt vmcnt(1)
	v_lshlrev_b32_e32 v152, 16, v160
	v_and_b32_e32 v153, 0xffff0000, v160
	v_lshlrev_b32_e32 v154, 16, v161
	v_and_b32_e32 v155, 0xffff0000, v161
	s_waitcnt vmcnt(0)
	v_lshlrev_b32_e32 v160, 16, v164
	v_and_b32_e32 v161, 0xffff0000, v164
	v_pk_fma_f32 v[96:97], v[96:97], v[160:161], v[152:153]
	v_or_b32_e32 v152, 48, v146
	v_ashrrev_i32_e32 v153, 31, v152
	v_lshlrev_b64 v[152:153], 10, v[152:153]
	v_lshlrev_b32_e32 v156, 16, v162
	v_and_b32_e32 v157, 0xffff0000, v162
	v_lshlrev_b32_e32 v158, 16, v163
	v_and_b32_e32 v159, 0xffff0000, v163
	v_lshlrev_b32_e32 v162, 16, v165
	v_and_b32_e32 v163, 0xffff0000, v165
	v_lshlrev_b32_e32 v164, 16, v166
	v_and_b32_e32 v165, 0xffff0000, v166
	v_lshl_add_u64 v[152:153], v[152:153], 0, v[144:145]
	v_lshlrev_b32_e32 v166, 16, v167
	v_and_b32_e32 v167, 0xffff0000, v167
	v_pk_fma_f32 v[100:101], v[100:101], v[164:165], v[156:157]
	v_lshlrev_b64 v[156:157], 1, v[152:153]
	v_pk_fma_f32 v[104:105], v[104:105], v[172:173], v[168:169]
	v_pk_fma_f32 v[108:109], v[108:109], v[174:175], v[170:171]
	v_pk_fma_f32 v[98:99], v[98:99], v[162:163], v[154:155]
	v_pk_fma_f32 v[102:103], v[102:103], v[166:167], v[158:159]
	v_lshl_add_u64 v[160:161], s[8:9], 0, v[156:157]
	global_load_dwordx4 v[152:155], v[160:161], off
	v_lshl_add_u64 v[164:165], s[0:1], 0, v[156:157]
	global_load_dwordx4 v[156:159], v[164:165], off
	s_nop 0
	global_load_dwordx4 v[160:163], v[160:161], off offset:256
	s_nop 0
	global_load_dwordx4 v[164:167], v[164:165], off offset:256
	v_exp_f32_e32 v147, v121
	v_exp_f32_e32 v125, v125
	v_pk_add_f32 v[116:117], v[116:117], v[140:141]
	v_pk_add_f32 v[112:113], v[112:113], v[136:137]
	v_mul_f32_e32 v116, 0xbfb8aa3b, v116
	v_mul_f32_e32 v112, 0xbfb8aa3b, v112
	v_pk_add_f32 v[126:127], v[126:127], v[134:135]
	v_rcp_f32_e32 v176, v124
	v_add_f32_e32 v124, 1.0, v147
	v_exp_f32_e32 v116, v116
	v_exp_f32_e32 v147, v112
	v_pk_add_f32 v[122:123], v[122:123], v[130:131]
	v_add_f32_e32 v121, 1.0, v125
	v_mul_f32_e32 v125, 0xbfb8aa3b, v126
	v_exp_f32_e32 v125, v125
	v_mul_f32_e32 v122, 0xbfb8aa3b, v122
	v_exp_f32_e32 v126, v122
	v_mul_f32_e32 v117, 0xbfb8aa3b, v117
	v_mul_f32_e32 v113, 0xbfb8aa3b, v113
	v_add_f32_e32 v112, 1.0, v116
	v_add_f32_e32 v116, 1.0, v147
	v_exp_f32_e32 v117, v117
	v_exp_f32_e32 v147, v113
	v_pk_add_f32 v[118:119], v[118:119], v[142:143]
	v_pk_add_f32 v[114:115], v[114:115], v[138:139]
	v_add_f32_e32 v122, 1.0, v125
	v_mul_f32_e32 v125, 0xbfb8aa3b, v127
	v_mul_f32_e32 v123, 0xbfb8aa3b, v123
	v_rcp_f32_e32 v177, v124
	v_add_f32_e32 v124, 1.0, v126
	v_exp_f32_e32 v125, v125
	v_exp_f32_e32 v126, v123
	v_mul_f32_e32 v118, 0xbfb8aa3b, v118
	v_mul_f32_e32 v114, 0xbfb8aa3b, v114
	v_add_f32_e32 v113, 1.0, v117
	v_add_f32_e32 v117, 1.0, v147
	v_exp_f32_e32 v118, v118
	v_exp_f32_e32 v147, v114
	v_rcp_f32_e32 v178, v124
	v_add_f32_e32 v123, 1.0, v125
	v_add_f32_e32 v124, 1.0, v126
	v_mul_f32_e32 v119, 0xbfb8aa3b, v119
	v_mul_f32_e32 v115, 0xbfb8aa3b, v115
	v_rcp_f32_e32 v122, v122
	v_rcp_f32_e32 v123, v123
	v_rcp_f32_e32 v179, v124
	v_add_f32_e32 v114, 1.0, v118
	v_add_f32_e32 v118, 1.0, v147
	v_exp_f32_e32 v119, v119
	v_exp_f32_e32 v147, v115
	v_rcp_f32_e32 v112, v112
	v_rcp_f32_e32 v113, v113
	v_add_f32_e32 v115, 1.0, v119
	v_add_f32_e32 v119, 1.0, v147
	v_rcp_f32_e32 v120, v120
	v_rcp_f32_e32 v121, v121
	v_rcp_f32_e32 v116, v116
	v_rcp_f32_e32 v117, v117
	v_rcp_f32_e32 v114, v114
	v_rcp_f32_e32 v118, v118
	v_rcp_f32_e32 v115, v115
	v_rcp_f32_e32 v119, v119
	v_pk_add_f32 v[92:93], v[92:93], v[132:133]
	v_pk_add_f32 v[80:81], v[80:81], v[128:129]
	v_mul_f32_e32 v92, 0xbfb8aa3b, v92
	v_mul_f32_e32 v80, 0xbfb8aa3b, v80
	v_exp_f32_e32 v92, v92
	v_exp_f32_e32 v147, v80
	v_mul_f32_e32 v93, 0xbfb8aa3b, v93
	v_mul_f32_e32 v81, 0xbfb8aa3b, v81
	v_add_f32_e32 v80, 1.0, v92
	v_add_f32_e32 v92, 1.0, v147
	v_exp_f32_e32 v93, v93
	v_exp_f32_e32 v147, v81
	v_pk_add_f32 v[76:77], v[76:77], v[140:141]
	v_pk_add_f32 v[72:73], v[72:73], v[136:137]
	v_pk_add_f32 v[94:95], v[94:95], v[134:135]
	s_waitcnt vmcnt(3)
	v_lshlrev_b32_e32 v168, 16, v152
	v_and_b32_e32 v169, 0xffff0000, v152
	v_lshlrev_b32_e32 v152, 16, v153
	v_and_b32_e32 v153, 0xffff0000, v153
	v_lshlrev_b32_e32 v170, 16, v154
	v_and_b32_e32 v171, 0xffff0000, v154
	v_lshlrev_b32_e32 v154, 16, v155
	v_and_b32_e32 v155, 0xffff0000, v155
	s_waitcnt vmcnt(2)
	v_lshlrev_b32_e32 v172, 16, v156
	v_and_b32_e32 v173, 0xffff0000, v156
	v_lshlrev_b32_e32 v156, 16, v157
	v_and_b32_e32 v157, 0xffff0000, v157
	v_lshlrev_b32_e32 v174, 16, v158
	v_and_b32_e32 v175, 0xffff0000, v158
	v_lshlrev_b32_e32 v158, 16, v159
	v_and_b32_e32 v159, 0xffff0000, v159
	v_pk_fma_f32 v[126:127], v[122:123], v[156:157], v[152:153]
	v_pk_fma_f32 v[122:123], v[178:179], v[158:159], v[154:155]
	s_waitcnt vmcnt(1)
	v_lshlrev_b32_e32 v152, 16, v160
	v_and_b32_e32 v153, 0xffff0000, v160
	v_lshlrev_b32_e32 v154, 16, v161
	v_and_b32_e32 v155, 0xffff0000, v161
	s_waitcnt vmcnt(0)
;     __device__ __forceinline__ void fused(f32x4 (&acc)[2][2][4][2], const Unit& u, int wr, int wc, int fr, int fq, PG8_LAS unsigned char* lds, int wid, int lane) const {
;     ...
;         for (int ai = 0; ai < 2; ++ai)
; #pragma unroll
;             for (int m = 0; m < 4; ++m) { const size_t off = (size_t)(u.pm * BM + ai * HALF + wr * 64 + m * 16 + fr) * 1024 + col0;
; #pragma unroll
;                 for (int bj = 0; bj < 2; ++bj) {
;                     const u32x4 xw = *(const u32x4*)(x1b + off + bj * HALF);
;                     f32x4 x0, x1;
;                     x0[0] = __uint_as_float(xw.x << 16); x0[1] = __uint_as_float(xw.x & 0xffff0000u); x0[2] = __uint_as_float(xw.y << 16); x0[3] = __uint_as_float(xw.y & 0xffff0000u);
;                     x1[0] = __uint_as_float(xw.z << 16); x1[1] = __uint_as_float(xw.z & 0xffff0000u); x1[2] = __uint_as_float(xw.w << 16); x1[3] = __uint_as_float(xw.w & 0xffff0000u);
;                     const u32x4 pw = *(const u32x4*)(pp + off + bj * HALF);
;                     f32x4 p0, p1;
;                     p0[0] = __uint_as_float(pw.x << 16); p0[1] = __uint_as_float(pw.x & 0xffff0000u); p0[2] = __uint_as_float(pw.y << 16); p0[3] = __uint_as_float(pw.y & 0xffff0000u);
;                     p1[0] = __uint_as_float(pw.z << 16); p1[1] = __uint_as_float(pw.z & 0xffff0000u); p1[2] = __uint_as_float(pw.w << 16); p1[3] = __uint_as_float(pw.w & 0xffff0000u);
;                     f32x4 g0 = acc[ai][bj][m][0], g1 = acc[ai][bj][m][1];
; #pragma unroll
;                     for (int e = 0; e < 4; ++e) { g0[e] = __builtin_amdgcn_rcpf(1.f + __expf(-g0[e])); g1[e] = __builtin_amdgcn_rcpf(1.f + __expf(-g1[e])); }
;                     acc[ai][bj][m][0] = x0 + g0 * p0; acc[ai][bj][m][1] = x1 + g1 * p1; }
	v_lshlrev_b32_e32 v160, 16, v164
	v_and_b32_e32 v161, 0xffff0000, v164
	v_pk_fma_f32 v[112:113], v[112:113], v[160:161], v[152:153]
	v_add_u32_e32 v152, 0x80, v146
	v_ashrrev_i32_e32 v153, 31, v152
	v_lshlrev_b64 v[152:153], 10, v[152:153]
	v_lshlrev_b32_e32 v156, 16, v162
	v_and_b32_e32 v157, 0xffff0000, v162
	v_lshlrev_b32_e32 v158, 16, v163
	v_and_b32_e32 v159, 0xffff0000, v163
	v_lshlrev_b32_e32 v162, 16, v165
	v_and_b32_e32 v163, 0xffff0000, v165
	v_lshlrev_b32_e32 v164, 16, v166
	v_and_b32_e32 v165, 0xffff0000, v166
	v_lshlrev_b32_e32 v166, 16, v167
	v_and_b32_e32 v167, 0xffff0000, v167
	v_lshl_add_u64 v[152:153], v[152:153], 0, v[144:145]
	v_pk_fma_f32 v[124:125], v[120:121], v[172:173], v[168:169]
	v_pk_fma_f32 v[120:121], v[176:177], v[174:175], v[170:171]
	v_pk_fma_f32 v[114:115], v[114:115], v[162:163], v[154:155]
	v_pk_fma_f32 v[116:117], v[116:117], v[164:165], v[156:157]
	v_pk_fma_f32 v[118:119], v[118:119], v[166:167], v[158:159]
	v_lshlrev_b64 v[156:157], 1, v[152:153]
	v_lshl_add_u64 v[160:161], s[8:9], 0, v[156:157]
	global_load_dwordx4 v[152:155], v[160:161], off
	v_lshl_add_u64 v[164:165], s[0:1], 0, v[156:157]
	global_load_dwordx4 v[156:159], v[164:165], off
	s_nop 0
	global_load_dwordx4 v[160:163], v[160:161], off offset:256
	s_nop 0
	global_load_dwordx4 v[164:167], v[164:165], off offset:256
	v_mul_f32_e32 v76, 0xbfb8aa3b, v76
	v_mul_f32_e32 v72, 0xbfb8aa3b, v72
	v_pk_add_f32 v[82:83], v[82:83], v[130:131]
	v_rcp_f32_e32 v176, v92
	v_add_f32_e32 v81, 1.0, v93
	v_add_f32_e32 v92, 1.0, v147
	v_mul_f32_e32 v93, 0xbfb8aa3b, v94
	v_exp_f32_e32 v76, v76
	v_exp_f32_e32 v147, v72
	v_exp_f32_e32 v93, v93
	v_mul_f32_e32 v82, 0xbfb8aa3b, v82
	v_exp_f32_e32 v94, v82
	v_mul_f32_e32 v77, 0xbfb8aa3b, v77
	v_mul_f32_e32 v73, 0xbfb8aa3b, v73
	v_add_f32_e32 v72, 1.0, v76
	v_add_f32_e32 v76, 1.0, v147
	v_exp_f32_e32 v77, v77
	v_exp_f32_e32 v147, v73
	v_add_f32_e32 v82, 1.0, v93
	v_mul_f32_e32 v93, 0xbfb8aa3b, v95
	v_mul_f32_e32 v83, 0xbfb8aa3b, v83
	v_pk_add_f32 v[78:79], v[78:79], v[142:143]
	v_pk_add_f32 v[74:75], v[74:75], v[138:139]
	v_rcp_f32_e32 v177, v92
	v_add_f32_e32 v92, 1.0, v94
	v_exp_f32_e32 v93, v93
	v_exp_f32_e32 v94, v83
	v_mul_f32_e32 v78, 0xbfb8aa3b, v78
	v_mul_f32_e32 v74, 0xbfb8aa3b, v74
	v_add_f32_e32 v73, 1.0, v77
	v_add_f32_e32 v77, 1.0, v147
	v_exp_f32_e32 v78, v78
	v_exp_f32_e32 v147, v74
	v_rcp_f32_e32 v178, v92
	v_add_f32_e32 v83, 1.0, v93
	v_add_f32_e32 v92, 1.0, v94
	v_rcp_f32_e32 v82, v82
	v_rcp_f32_e32 v83, v83
	v_rcp_f32_e32 v179, v92
	v_mul_f32_e32 v79, 0xbfb8aa3b, v79
	v_mul_f32_e32 v75, 0xbfb8aa3b, v75
	v_rcp_f32_e32 v72, v72
	v_rcp_f32_e32 v73, v73
	v_add_f32_e32 v74, 1.0, v78
	v_add_f32_e32 v78, 1.0, v147
	v_exp_f32_e32 v79, v79
	v_exp_f32_e32 v147, v75
	v_rcp_f32_e32 v76, v76
	v_rcp_f32_e32 v77, v77
	v_add_f32_e32 v75, 1.0, v79
	v_add_f32_e32 v79, 1.0, v147
	v_rcp_f32_e32 v80, v80
	v_rcp_f32_e32 v81, v81
	v_rcp_f32_e32 v74, v74
	v_rcp_f32_e32 v78, v78
	v_rcp_f32_e32 v75, v75
	v_rcp_f32_e32 v79, v79
	v_pk_add_f32 v[52:53], v[52:53], v[132:133]
	v_pk_add_f32 v[48:49], v[48:49], v[128:129]
	v_mul_f32_e32 v52, 0xbfb8aa3b, v52
	v_mul_f32_e32 v48, 0xbfb8aa3b, v48
	v_exp_f32_e32 v52, v52
	v_exp_f32_e32 v147, v48
	v_mul_f32_e32 v53, 0xbfb8aa3b, v53
	v_mul_f32_e32 v49, 0xbfb8aa3b, v49
	v_add_f32_e32 v48, 1.0, v52
	v_add_f32_e32 v52, 1.0, v147
	v_exp_f32_e32 v53, v53
	v_exp_f32_e32 v147, v49
	v_pk_add_f32 v[44:45], v[44:45], v[140:141]
	v_pk_add_f32 v[40:41], v[40:41], v[136:137]
	v_pk_add_f32 v[54:55], v[54:55], v[134:135]
	v_mul_f32_e32 v44, 0xbfb8aa3b, v44
	v_mul_f32_e32 v40, 0xbfb8aa3b, v40
	v_pk_add_f32 v[50:51], v[50:51], v[130:131]
	v_add_f32_e32 v49, 1.0, v53
	v_mul_f32_e32 v53, 0xbfb8aa3b, v54
	s_waitcnt vmcnt(3)
	v_lshlrev_b32_e32 v168, 16, v152
	v_and_b32_e32 v169, 0xffff0000, v152
	v_lshlrev_b32_e32 v152, 16, v153
	v_and_b32_e32 v153, 0xffff0000, v153
	v_lshlrev_b32_e32 v170, 16, v154
	v_and_b32_e32 v171, 0xffff0000, v154
	v_lshlrev_b32_e32 v154, 16, v155
	v_and_b32_e32 v155, 0xffff0000, v155
	s_waitcnt vmcnt(2)
	v_lshlrev_b32_e32 v172, 16, v156
	v_and_b32_e32 v173, 0xffff0000, v156
	v_lshlrev_b32_e32 v156, 16, v157
	v_and_b32_e32 v157, 0xffff0000, v157
	v_lshlrev_b32_e32 v174, 16, v158
	v_and_b32_e32 v175, 0xffff0000, v158
	v_lshlrev_b32_e32 v158, 16, v159
	v_and_b32_e32 v159, 0xffff0000, v159
	v_pk_fma_f32 v[94:95], v[82:83], v[156:157], v[152:153]
	v_pk_fma_f32 v[82:83], v[178:179], v[158:159], v[154:155]
	s_waitcnt vmcnt(1)
	v_lshlrev_b32_e32 v152, 16, v160
	v_and_b32_e32 v153, 0xffff0000, v160
	v_lshlrev_b32_e32 v154, 16, v161
	v_and_b32_e32 v155, 0xffff0000, v161
	s_waitcnt vmcnt(0)
;     __device__ __forceinline__ void fused(f32x4 (&acc)[2][2][4][2], const Unit& u, int wr, int wc, int fr, int fq, PG8_LAS unsigned char* lds, int wid, int lane) const {
;     ...
;         for (int ai = 0; ai < 2; ++ai)
; #pragma unroll
;             for (int m = 0; m < 4; ++m) { const size_t off = (size_t)(u.pm * BM + ai * HALF + wr * 64 + m * 16 + fr) * 1024 + col0;
; #pragma unroll
;                 for (int bj = 0; bj < 2; ++bj) {
;                     const u32x4 xw = *(const u32x4*)(x1b + off + bj * HALF);
;                     f32x4 x0, x1;
;                     x0[0] = __uint_as_float(xw.x << 16); x0[1] = __uint_as_float(xw.x & 0xffff0000u); x0[2] = __uint_as_float(xw.y << 16); x0[3] = __uint_as_float(xw.y & 0xffff0000u);
;                     x1[0] = __uint_as_float(xw.z << 16); x1[1] = __uint_as_float(xw.z & 0xffff0000u); x1[2] = __uint_as_float(xw.w << 16); x1[3] = __uint_as_float(xw.w & 0xffff0000u);
;                     const u32x4 pw = *(const u32x4*)(pp + off + bj * HALF);
;                     f32x4 p0, p1;
;                     p0[0] = __uint_as_float(pw.x << 16); p0[1] = __uint_as_float(pw.x & 0xffff0000u); p0[2] = __uint_as_float(pw.y << 16); p0[3] = __uint_as_float(pw.y & 0xffff0000u);
;                     p1[0] = __uint_as_float(pw.z << 16); p1[1] = __uint_as_float(pw.z & 0xffff0000u); p1[2] = __uint_as_float(pw.w << 16); p1[3] = __uint_as_float(pw.w & 0xffff0000u);
;                     f32x4 g0 = acc[ai][bj][m][0], g1 = acc[ai][bj][m][1];
; #pragma unroll
;                     for (int e = 0; e < 4; ++e) { g0[e] = __builtin_amdgcn_rcpf(1.f + __expf(-g0[e])); g1[e] = __builtin_amdgcn_rcpf(1.f + __expf(-g1[e])); }
;                     acc[ai][bj][m][0] = x0 + g0 * p0; acc[ai][bj][m][1] = x1 + g1 * p1; }
	v_lshlrev_b32_e32 v160, 16, v164
	v_and_b32_e32 v161, 0xffff0000, v164
	v_pk_fma_f32 v[72:73], v[72:73], v[160:161], v[152:153]
	v_add_u32_e32 v152, 0x90, v146
	v_ashrrev_i32_e32 v153, 31, v152
	v_lshlrev_b64 v[152:153], 10, v[152:153]
	v_lshlrev_b32_e32 v156, 16, v162
	v_and_b32_e32 v157, 0xffff0000, v162
	v_lshlrev_b32_e32 v158, 16, v163
	v_and_b32_e32 v159, 0xffff0000, v163
	v_lshlrev_b32_e32 v162, 16, v165
	v_and_b32_e32 v163, 0xffff0000, v165
	v_lshlrev_b32_e32 v164, 16, v166
	v_and_b32_e32 v165, 0xffff0000, v166
	v_lshl_add_u64 v[152:153], v[152:153], 0, v[144:145]
	v_lshlrev_b32_e32 v166, 16, v167
	v_and_b32_e32 v167, 0xffff0000, v167
	v_pk_fma_f32 v[76:77], v[76:77], v[164:165], v[156:157]
	v_lshlrev_b64 v[156:157], 1, v[152:153]
	v_pk_fma_f32 v[92:93], v[80:81], v[172:173], v[168:169]
	v_pk_fma_f32 v[80:81], v[176:177], v[174:175], v[170:171]
	v_pk_fma_f32 v[74:75], v[74:75], v[162:163], v[154:155]
	v_pk_fma_f32 v[78:79], v[78:79], v[166:167], v[158:159]
	v_lshl_add_u64 v[160:161], s[8:9], 0, v[156:157]
	global_load_dwordx4 v[152:155], v[160:161], off
	v_lshl_add_u64 v[164:165], s[0:1], 0, v[156:157]
	global_load_dwordx4 v[156:159], v[164:165], off
	s_nop 0
	global_load_dwordx4 v[160:163], v[160:161], off offset:256
	s_nop 0
	global_load_dwordx4 v[164:167], v[164:165], off offset:256
	v_rcp_f32_e32 v176, v52
	v_add_f32_e32 v52, 1.0, v147
	v_exp_f32_e32 v44, v44
	v_exp_f32_e32 v147, v40
	v_exp_f32_e32 v53, v53
	v_mul_f32_e32 v50, 0xbfb8aa3b, v50
	v_exp_f32_e32 v54, v50
	v_mul_f32_e32 v45, 0xbfb8aa3b, v45
	v_mul_f32_e32 v41, 0xbfb8aa3b, v41
	v_add_f32_e32 v40, 1.0, v44
	v_add_f32_e32 v44, 1.0, v147
	v_exp_f32_e32 v45, v45
	v_exp_f32_e32 v147, v41
	v_add_f32_e32 v50, 1.0, v53
	v_mul_f32_e32 v53, 0xbfb8aa3b, v55
	v_mul_f32_e32 v51, 0xbfb8aa3b, v51
	v_pk_add_f32 v[46:47], v[46:47], v[142:143]
	v_pk_add_f32 v[42:43], v[42:43], v[138:139]
	v_rcp_f32_e32 v177, v52
	v_add_f32_e32 v52, 1.0, v54
	v_exp_f32_e32 v53, v53
	v_exp_f32_e32 v54, v51
	v_mul_f32_e32 v46, 0xbfb8aa3b, v46
	v_mul_f32_e32 v42, 0xbfb8aa3b, v42
	v_add_f32_e32 v41, 1.0, v45
	v_add_f32_e32 v45, 1.0, v147
	v_exp_f32_e32 v46, v46
	v_exp_f32_e32 v147, v42
	v_rcp_f32_e32 v178, v52
	v_add_f32_e32 v51, 1.0, v53
	v_add_f32_e32 v52, 1.0, v54
	v_rcp_f32_e32 v50, v50
	v_rcp_f32_e32 v51, v51
	v_rcp_f32_e32 v179, v52
	v_mul_f32_e32 v47, 0xbfb8aa3b, v47
	v_mul_f32_e32 v43, 0xbfb8aa3b, v43
	v_rcp_f32_e32 v40, v40
	v_rcp_f32_e32 v41, v41
	v_add_f32_e32 v42, 1.0, v46
	v_add_f32_e32 v46, 1.0, v147
	v_exp_f32_e32 v47, v47
	v_exp_f32_e32 v147, v43
	v_rcp_f32_e32 v44, v44
	v_rcp_f32_e32 v45, v45
	v_add_f32_e32 v43, 1.0, v47
	v_add_f32_e32 v47, 1.0, v147
	v_rcp_f32_e32 v48, v48
	v_rcp_f32_e32 v49, v49
	v_rcp_f32_e32 v42, v42
	v_rcp_f32_e32 v46, v46
	v_rcp_f32_e32 v43, v43
	v_rcp_f32_e32 v47, v47
	v_pk_add_f32 v[28:29], v[28:29], v[132:133]
	v_pk_add_f32 v[24:25], v[24:25], v[128:129]
	v_mul_f32_e32 v28, 0xbfb8aa3b, v28
	v_mul_f32_e32 v24, 0xbfb8aa3b, v24
	v_exp_f32_e32 v28, v28
	v_exp_f32_e32 v147, v24
	v_mul_f32_e32 v25, 0xbfb8aa3b, v25
	v_pk_add_f32 v[20:21], v[20:21], v[140:141]
	v_add_f32_e32 v24, 1.0, v28
	v_add_f32_e32 v28, 1.0, v147
	v_exp_f32_e32 v147, v25
	v_pk_add_f32 v[16:17], v[16:17], v[136:137]
	v_mul_f32_e32 v20, 0xbfb8aa3b, v20
	v_mul_f32_e32 v16, 0xbfb8aa3b, v16
	v_mul_f32_e32 v29, 0xbfb8aa3b, v29
	v_exp_f32_e32 v20, v20
	v_exp_f32_e32 v29, v29
	v_mul_f32_e32 v21, 0xbfb8aa3b, v21
	v_mul_f32_e32 v17, 0xbfb8aa3b, v17
	v_pk_add_f32 v[30:31], v[30:31], v[134:135]
	v_exp_f32_e32 v21, v21
	v_pk_add_f32 v[26:27], v[26:27], v[130:131]
	v_add_f32_e32 v25, 1.0, v29
	v_mul_f32_e32 v29, 0xbfb8aa3b, v30
	v_pk_add_f32 v[22:23], v[22:23], v[142:143]
	s_waitcnt vmcnt(3)
	v_lshlrev_b32_e32 v168, 16, v152
	v_and_b32_e32 v169, 0xffff0000, v152
	v_lshlrev_b32_e32 v152, 16, v153
	v_and_b32_e32 v153, 0xffff0000, v153
	v_lshlrev_b32_e32 v170, 16, v154
	v_and_b32_e32 v171, 0xffff0000, v154
	v_lshlrev_b32_e32 v154, 16, v155
	v_and_b32_e32 v155, 0xffff0000, v155
	s_waitcnt vmcnt(2)
	v_lshlrev_b32_e32 v172, 16, v156
	v_and_b32_e32 v173, 0xffff0000, v156
	v_lshlrev_b32_e32 v156, 16, v157
	v_and_b32_e32 v157, 0xffff0000, v157
	v_lshlrev_b32_e32 v174, 16, v158
	v_and_b32_e32 v175, 0xffff0000, v158
	v_lshlrev_b32_e32 v158, 16, v159
	v_and_b32_e32 v159, 0xffff0000, v159
	v_pk_fma_f32 v[54:55], v[50:51], v[156:157], v[152:153]
	v_pk_fma_f32 v[50:51], v[178:179], v[158:159], v[154:155]
	s_waitcnt vmcnt(1)
	v_lshlrev_b32_e32 v152, 16, v160
	v_and_b32_e32 v153, 0xffff0000, v160
	v_lshlrev_b32_e32 v154, 16, v161
	v_and_b32_e32 v155, 0xffff0000, v161
	s_waitcnt vmcnt(0)
;     __device__ __forceinline__ void fused(f32x4 (&acc)[2][2][4][2], const Unit& u, int wr, int wc, int fr, int fq, PG8_LAS unsigned char* lds, int wid, int lane) const {
;     ...
;         for (int ai = 0; ai < 2; ++ai)
; #pragma unroll
;             for (int m = 0; m < 4; ++m) { const size_t off = (size_t)(u.pm * BM + ai * HALF + wr * 64 + m * 16 + fr) * 1024 + col0;
; #pragma unroll
;                 for (int bj = 0; bj < 2; ++bj) {
;                     const u32x4 xw = *(const u32x4*)(x1b + off + bj * HALF);
;                     f32x4 x0, x1;
;                     x0[0] = __uint_as_float(xw.x << 16); x0[1] = __uint_as_float(xw.x & 0xffff0000u); x0[2] = __uint_as_float(xw.y << 16); x0[3] = __uint_as_float(xw.y & 0xffff0000u);
;                     x1[0] = __uint_as_float(xw.z << 16); x1[1] = __uint_as_float(xw.z & 0xffff0000u); x1[2] = __uint_as_float(xw.w << 16); x1[3] = __uint_as_float(xw.w & 0xffff0000u);
;                     const u32x4 pw = *(const u32x4*)(pp + off + bj * HALF);
;                     f32x4 p0, p1;
;                     p0[0] = __uint_as_float(pw.x << 16); p0[1] = __uint_as_float(pw.x & 0xffff0000u); p0[2] = __uint_as_float(pw.y << 16); p0[3] = __uint_as_float(pw.y & 0xffff0000u);
;                     p1[0] = __uint_as_float(pw.z << 16); p1[1] = __uint_as_float(pw.z & 0xffff0000u); p1[2] = __uint_as_float(pw.w << 16); p1[3] = __uint_as_float(pw.w & 0xffff0000u);
;                     f32x4 g0 = acc[ai][bj][m][0], g1 = acc[ai][bj][m][1];
; #pragma unroll
;                     for (int e = 0; e < 4; ++e) { g0[e] = __builtin_amdgcn_rcpf(1.f + __expf(-g0[e])); g1[e] = __builtin_amdgcn_rcpf(1.f + __expf(-g1[e])); }
;                     acc[ai][bj][m][0] = x0 + g0 * p0; acc[ai][bj][m][1] = x1 + g1 * p1; }
	v_lshlrev_b32_e32 v160, 16, v164
	v_and_b32_e32 v161, 0xffff0000, v164
	v_pk_fma_f32 v[40:41], v[40:41], v[160:161], v[152:153]
	v_add_u32_e32 v152, 0xa0, v146
	v_ashrrev_i32_e32 v153, 31, v152
	v_lshlrev_b64 v[152:153], 10, v[152:153]
	v_lshlrev_b32_e32 v156, 16, v162
	v_and_b32_e32 v157, 0xffff0000, v162
	v_lshlrev_b32_e32 v158, 16, v163
	v_and_b32_e32 v159, 0xffff0000, v163
	v_lshlrev_b32_e32 v162, 16, v165
	v_and_b32_e32 v163, 0xffff0000, v165
	v_lshlrev_b32_e32 v164, 16, v166
	v_and_b32_e32 v165, 0xffff0000, v166
	v_lshl_add_u64 v[152:153], v[152:153], 0, v[144:145]
	v_lshlrev_b32_e32 v166, 16, v167
	v_and_b32_e32 v167, 0xffff0000, v167
	v_pk_fma_f32 v[44:45], v[44:45], v[164:165], v[156:157]
	v_lshlrev_b64 v[156:157], 1, v[152:153]
	v_pk_fma_f32 v[52:53], v[48:49], v[172:173], v[168:169]
	v_pk_fma_f32 v[48:49], v[176:177], v[174:175], v[170:171]
	v_pk_fma_f32 v[42:43], v[42:43], v[162:163], v[154:155]
	v_pk_fma_f32 v[46:47], v[46:47], v[166:167], v[158:159]
	v_lshl_add_u64 v[160:161], s[8:9], 0, v[156:157]
	global_load_dwordx4 v[152:155], v[160:161], off
	v_lshl_add_u64 v[164:165], s[0:1], 0, v[156:157]
	global_load_dwordx4 v[156:159], v[164:165], off
	s_nop 0
	global_load_dwordx4 v[160:163], v[160:161], off offset:256
	s_nop 0
	global_load_dwordx4 v[164:167], v[164:165], off offset:256
	v_rcp_f32_e32 v176, v28
	v_add_f32_e32 v28, 1.0, v147
	v_exp_f32_e32 v147, v16
	v_add_f32_e32 v16, 1.0, v20
	v_pk_add_f32 v[18:19], v[18:19], v[138:139]
	v_exp_f32_e32 v29, v29
	v_add_f32_e32 v20, 1.0, v147
	v_exp_f32_e32 v147, v17
	v_mul_f32_e32 v26, 0xbfb8aa3b, v26
	v_exp_f32_e32 v30, v26
	v_mul_f32_e32 v22, 0xbfb8aa3b, v22
	v_mul_f32_e32 v18, 0xbfb8aa3b, v18
	v_add_f32_e32 v17, 1.0, v21
	v_add_f32_e32 v21, 1.0, v147
	v_exp_f32_e32 v22, v22
	v_exp_f32_e32 v147, v18
	v_add_f32_e32 v26, 1.0, v29
	v_mul_f32_e32 v29, 0xbfb8aa3b, v31
	v_mul_f32_e32 v27, 0xbfb8aa3b, v27
	v_rcp_f32_e32 v177, v28
	v_add_f32_e32 v28, 1.0, v30
	v_exp_f32_e32 v29, v29
	v_exp_f32_e32 v30, v27
	v_mul_f32_e32 v23, 0xbfb8aa3b, v23
	v_mul_f32_e32 v19, 0xbfb8aa3b, v19
	v_add_f32_e32 v18, 1.0, v22
	v_add_f32_e32 v22, 1.0, v147
	v_exp_f32_e32 v23, v23
	v_exp_f32_e32 v147, v19
	v_rcp_f32_e32 v178, v28
	v_add_f32_e32 v27, 1.0, v29
	v_add_f32_e32 v28, 1.0, v30
	v_rcp_f32_e32 v26, v26
	v_rcp_f32_e32 v27, v27
	v_rcp_f32_e32 v179, v28
	v_add_f32_e32 v19, 1.0, v23
	v_add_f32_e32 v23, 1.0, v147
	v_add_u32_e32 v146, 0xb0, v146
	v_rcp_f32_e32 v24, v24
	v_rcp_f32_e32 v25, v25
	v_rcp_f32_e32 v16, v16
	v_rcp_f32_e32 v20, v20
	v_rcp_f32_e32 v17, v17
	v_rcp_f32_e32 v21, v21
	v_rcp_f32_e32 v18, v18
	v_rcp_f32_e32 v22, v22
	v_rcp_f32_e32 v19, v19
	v_rcp_f32_e32 v23, v23
	v_ashrrev_i32_e32 v147, 31, v146
	v_lshlrev_b64 v[146:147], 10, v[146:147]
	v_lshl_add_u64 v[146:147], v[146:147], 0, v[144:145]
	v_lshlrev_b64 v[146:147], 1, v[146:147]
	v_pk_add_f32 v[12:13], v[12:13], v[132:133]
	v_pk_add_f32 v[8:9], v[8:9], v[128:129]
	v_mul_f32_e32 v13, 0xbfb8aa3b, v13
	v_exp_f32_e32 v13, v13
	v_mul_f32_e32 v12, 0xbfb8aa3b, v12
	v_mul_f32_e32 v8, 0xbfb8aa3b, v8
	v_pk_add_f32 v[14:15], v[14:15], v[134:135]
	v_pk_add_f32 v[10:11], v[10:11], v[130:131]
	v_exp_f32_e32 v12, v12
	v_mul_f32_e32 v9, 0xbfb8aa3b, v9
	v_mul_f32_e32 v10, 0xbfb8aa3b, v10
	v_mul_f32_e32 v11, 0xbfb8aa3b, v11
	v_pk_add_f32 v[4:5], v[4:5], v[140:141]
	v_pk_add_f32 v[0:1], v[0:1], v[136:137]
	v_mul_f32_e32 v4, 0xbfb8aa3b, v4
	v_mul_f32_e32 v0, 0xbfb8aa3b, v0
	v_exp_f32_e32 v4, v4
	v_mul_f32_e32 v5, 0xbfb8aa3b, v5
	v_mul_f32_e32 v1, 0xbfb8aa3b, v1
	v_exp_f32_e32 v5, v5
	v_pk_add_f32 v[6:7], v[6:7], v[142:143]
	v_pk_add_f32 v[2:3], v[2:3], v[138:139]
	v_mul_f32_e32 v6, 0xbfb8aa3b, v6
	v_mul_f32_e32 v2, 0xbfb8aa3b, v2
	v_exp_f32_e32 v6, v6
	s_waitcnt vmcnt(3)
	v_lshlrev_b32_e32 v168, 16, v152
	v_and_b32_e32 v169, 0xffff0000, v152
	v_lshlrev_b32_e32 v152, 16, v153
	v_and_b32_e32 v153, 0xffff0000, v153
	v_lshlrev_b32_e32 v170, 16, v154
	v_and_b32_e32 v171, 0xffff0000, v154
	v_lshlrev_b32_e32 v154, 16, v155
	v_and_b32_e32 v155, 0xffff0000, v155
	s_waitcnt vmcnt(2)
	v_lshlrev_b32_e32 v172, 16, v156
	v_and_b32_e32 v173, 0xffff0000, v156
	v_lshlrev_b32_e32 v156, 16, v157
	v_and_b32_e32 v157, 0xffff0000, v157
	v_lshlrev_b32_e32 v174, 16, v158
	v_and_b32_e32 v175, 0xffff0000, v158
	v_lshlrev_b32_e32 v158, 16, v159
	v_and_b32_e32 v159, 0xffff0000, v159
	v_pk_fma_f32 v[30:31], v[26:27], v[156:157], v[152:153]
	v_pk_fma_f32 v[26:27], v[178:179], v[158:159], v[154:155]
	s_waitcnt vmcnt(1)
;     __device__ __forceinline__ void fused(f32x4 (&acc)[2][2][4][2], const Unit& u, int wr, int wc, int fr, int fq, PG8_LAS unsigned char* lds, int wid, int lane) const {
;     ...
;         for (int ai = 0; ai < 2; ++ai)
; #pragma unroll
;             for (int m = 0; m < 4; ++m) { const size_t off = (size_t)(u.pm * BM + ai * HALF + wr * 64 + m * 16 + fr) * 1024 + col0;
; #pragma unroll
;                 for (int bj = 0; bj < 2; ++bj) {
;                     const u32x4 xw = *(const u32x4*)(x1b + off + bj * HALF);
;                     f32x4 x0, x1;
;                     x0[0] = __uint_as_float(xw.x << 16); x0[1] = __uint_as_float(xw.x & 0xffff0000u); x0[2] = __uint_as_float(xw.y << 16); x0[3] = __uint_as_float(xw.y & 0xffff0000u);
;                     x1[0] = __uint_as_float(xw.z << 16); x1[1] = __uint_as_float(xw.z & 0xffff0000u); x1[2] = __uint_as_float(xw.w << 16); x1[3] = __uint_as_float(xw.w & 0xffff0000u);
;                     const u32x4 pw = *(const u32x4*)(pp + off + bj * HALF);
;                     f32x4 p0, p1;
;                     p0[0] = __uint_as_float(pw.x << 16); p0[1] = __uint_as_float(pw.x & 0xffff0000u); p0[2] = __uint_as_float(pw.y << 16); p0[3] = __uint_as_float(pw.y & 0xffff0000u);
;                     p1[0] = __uint_as_float(pw.z << 16); p1[1] = __uint_as_float(pw.z & 0xffff0000u); p1[2] = __uint_as_float(pw.w << 16); p1[3] = __uint_as_float(pw.w & 0xffff0000u);
;                     f32x4 g0 = acc[ai][bj][m][0], g1 = acc[ai][bj][m][1];
; #pragma unroll
;                     for (int e = 0; e < 4; ++e) { g0[e] = __builtin_amdgcn_rcpf(1.f + __expf(-g0[e])); g1[e] = __builtin_amdgcn_rcpf(1.f + __expf(-g1[e])); }
;                     acc[ai][bj][m][0] = x0 + g0 * p0; acc[ai][bj][m][1] = x1 + g1 * p1; }
;                 asm volatile("" : "+v"(acc[ai][0][m][0]), "+v"(acc[ai][0][m][1]), "+v"(acc[ai][1][m][0]), "+v"(acc[ai][1][m][1]));
;                 if (m == 3) asm volatile("" ::: "memory"); }
;         if (dry) {
	v_lshlrev_b32_e32 v152, 16, v160
	v_and_b32_e32 v153, 0xffff0000, v160
	v_lshlrev_b32_e32 v154, 16, v161
	v_and_b32_e32 v155, 0xffff0000, v161
	v_lshlrev_b32_e32 v156, 16, v162
	v_and_b32_e32 v157, 0xffff0000, v162
	v_lshlrev_b32_e32 v158, 16, v163
	v_and_b32_e32 v159, 0xffff0000, v163
	s_waitcnt vmcnt(0)
	v_lshlrev_b32_e32 v160, 16, v164
	v_and_b32_e32 v161, 0xffff0000, v164
	v_lshlrev_b32_e32 v162, 16, v165
	v_and_b32_e32 v163, 0xffff0000, v165
	v_lshlrev_b32_e32 v164, 16, v166
	v_and_b32_e32 v165, 0xffff0000, v166
	v_lshlrev_b32_e32 v166, 16, v167
	v_and_b32_e32 v167, 0xffff0000, v167
	v_pk_fma_f32 v[28:29], v[24:25], v[172:173], v[168:169]
	v_pk_fma_f32 v[24:25], v[176:177], v[174:175], v[170:171]
	v_pk_fma_f32 v[16:17], v[16:17], v[160:161], v[152:153]
	v_pk_fma_f32 v[18:19], v[18:19], v[162:163], v[154:155]
	v_pk_fma_f32 v[20:21], v[20:21], v[164:165], v[156:157]
	v_pk_fma_f32 v[22:23], v[22:23], v[166:167], v[158:159]
	v_lshl_add_u64 v[160:161], s[8:9], 0, v[146:147]
	global_load_dwordx4 v[152:155], v[160:161], off
	v_lshl_add_u64 v[146:147], s[0:1], 0, v[146:147]
	global_load_dwordx4 v[156:159], v[146:147], off
	s_nop 0
	global_load_dwordx4 v[160:163], v[160:161], off offset:256
	s_nop 0
	global_load_dwordx4 v[164:167], v[146:147], off offset:256
	v_exp_f32_e32 v146, v8
	v_exp_f32_e32 v147, v9
	v_add_f32_e32 v9, 1.0, v13
	v_mul_f32_e32 v13, 0xbfb8aa3b, v14
	v_exp_f32_e32 v13, v13
	v_exp_f32_e32 v14, v10
	v_add_f32_e32 v8, 1.0, v12
	v_add_f32_e32 v12, 1.0, v146
	v_rcp_f32_e32 v146, v12
	v_add_f32_e32 v12, 1.0, v147
	v_rcp_f32_e32 v147, v12
	v_add_f32_e32 v10, 1.0, v13
	v_add_f32_e32 v12, 1.0, v14
	v_mul_f32_e32 v13, 0xbfb8aa3b, v15
	v_exp_f32_e32 v14, v11
	v_rcp_f32_e32 v8, v8
	v_rcp_f32_e32 v9, v9
	v_exp_f32_e32 v13, v13
	v_mul_f32_e32 v7, 0xbfb8aa3b, v7
	v_mul_f32_e32 v3, 0xbfb8aa3b, v3
	v_exp_f32_e32 v7, v7
	v_add_f32_e32 v11, 1.0, v13
	v_rcp_f32_e32 v10, v10
	v_rcp_f32_e32 v11, v11
	v_readlane_b32 s0, v252, 18
	v_readlane_b32 s1, v252, 19
	s_andn2_b64 vcc, exec, s[0:1]
	s_mov_b64 s[0:1], -1
	s_waitcnt vmcnt(3)
	v_lshlrev_b32_e32 v128, 16, v152
	v_and_b32_e32 v129, 0xffff0000, v152
	v_lshlrev_b32_e32 v132, 16, v154
	v_and_b32_e32 v133, 0xffff0000, v154
	s_waitcnt vmcnt(2)
	v_lshlrev_b32_e32 v136, 16, v156
	v_and_b32_e32 v137, 0xffff0000, v156
	v_lshlrev_b32_e32 v140, 16, v158
	v_and_b32_e32 v141, 0xffff0000, v158
	v_rcp_f32_e32 v152, v12
	v_add_f32_e32 v12, 1.0, v14
	v_lshlrev_b32_e32 v130, 16, v153
	v_and_b32_e32 v131, 0xffff0000, v153
	v_rcp_f32_e32 v153, v12
	v_pk_fma_f32 v[12:13], v[8:9], v[136:137], v[128:129]
	v_pk_fma_f32 v[8:9], v[146:147], v[140:141], v[132:133]
	v_exp_f32_e32 v146, v0
	v_add_f32_e32 v0, 1.0, v4
	v_rcp_f32_e32 v0, v0
	v_lshlrev_b32_e32 v134, 16, v155
	v_add_f32_e32 v4, 1.0, v146
	v_exp_f32_e32 v146, v1
	v_add_f32_e32 v1, 1.0, v5
	v_rcp_f32_e32 v4, v4
	v_rcp_f32_e32 v1, v1
	v_add_f32_e32 v5, 1.0, v146
	v_exp_f32_e32 v146, v2
	v_add_f32_e32 v2, 1.0, v6
	v_rcp_f32_e32 v5, v5
	v_rcp_f32_e32 v2, v2
	v_add_f32_e32 v6, 1.0, v146
	v_exp_f32_e32 v146, v3
	v_add_f32_e32 v3, 1.0, v7
	v_rcp_f32_e32 v6, v6
	v_rcp_f32_e32 v3, v3
	v_add_f32_e32 v7, 1.0, v146
	v_rcp_f32_e32 v7, v7
	v_and_b32_e32 v135, 0xffff0000, v155
	v_lshlrev_b32_e32 v138, 16, v157
	v_and_b32_e32 v139, 0xffff0000, v157
	v_lshlrev_b32_e32 v142, 16, v159
	v_and_b32_e32 v143, 0xffff0000, v159
	v_pk_fma_f32 v[14:15], v[10:11], v[138:139], v[130:131]
	v_pk_fma_f32 v[10:11], v[152:153], v[142:143], v[134:135]
	s_waitcnt vmcnt(1)
	v_lshlrev_b32_e32 v128, 16, v160
	v_and_b32_e32 v129, 0xffff0000, v160
	v_lshlrev_b32_e32 v130, 16, v161
	v_and_b32_e32 v131, 0xffff0000, v161
	v_lshlrev_b32_e32 v132, 16, v162
	v_and_b32_e32 v133, 0xffff0000, v162
	v_lshlrev_b32_e32 v134, 16, v163
	v_and_b32_e32 v135, 0xffff0000, v163
	s_waitcnt vmcnt(0)
	v_lshlrev_b32_e32 v136, 16, v164
	v_and_b32_e32 v137, 0xffff0000, v164
	v_lshlrev_b32_e32 v138, 16, v165
	v_and_b32_e32 v139, 0xffff0000, v165
	v_lshlrev_b32_e32 v140, 16, v166
	v_and_b32_e32 v141, 0xffff0000, v166
	v_lshlrev_b32_e32 v142, 16, v167
	v_and_b32_e32 v143, 0xffff0000, v167
	v_pk_fma_f32 v[0:1], v[0:1], v[136:137], v[128:129]
	v_pk_fma_f32 v[2:3], v[2:3], v[138:139], v[130:131]
	v_pk_fma_f32 v[4:5], v[4:5], v[140:141], v[132:133]
	v_pk_fma_f32 v[6:7], v[6:7], v[142:143], v[134:135]
	s_nop 0
	s_cbranch_vccnz .LBB0_993
	s_mov_b64 s[0:1], 0
